# GEMM main loops: per-segment s_setprio toggles removed, one static s_setprio 1 for waves 4-7 per GEMM phase (on v26)
# baseline (speedup 1.0000x reference)
; #define PG8_STAGE(bufoff, gbase, voff) do { _Pragma("unroll") for (int _i = 0; _i < 2; ++_i) \
;         __builtin_amdgcn_global_load_lds((const unsigned*)((const char*)(gbase) + (voff)[_i]), (LAS unsigned*)(lds + (bufoff) + ldsw + _i * 8192), 16, 0, 0); } while (0)
; #define PG8_BAR __builtin_amdgcn_s_barrier()
; template <bool BF16, class Epi, class Sched, bool ALIGN_EPI = true, bool SP2 = true>
; __device__ __forceinline__ void gemm_phase(LAS unsigned char* lds, const Gemm g, const Sched& S, const Epi& E) {
;     const int tid = threadIdx.x, wid = __builtin_amdgcn_readfirstlane(tid >> 6), lane = tid & 63, wr = wid >> 2, wc = wid & 3, fr = lane & 15, fq = lane >> 4;
;     const int K = g.K, nt = K / BK;
;     unsigned voffA[2], voffB[2];
; #pragma unroll
;     for (int i = 0; i < 2; ++i) { int R, C; stage_rc(tid * 16 + i * 8192, R, C); const int Rb = Epi::PERM ? ((R & ~31) + perm32(R & 31)) : R;
;         voffA[i] = (unsigned)(R * K + C) * 2u; voffB[i] = (unsigned)(Rb * K + C) * 2u; }
;     const size_t kstep = (size_t)(BK * 2);
;     const size_t hstep = (size_t)HALF * K * 2;
;     const size_t tstep = 2 * hstep;
;     const unsigned ldsw = (unsigned)wid * 1024u;
;     const int aoff = lds_byte(wr * 64 + fr, fq * 8), boff = lds_byte(wc * 32 + fr, fq * 8);
;     ...
;     Unit cur, nxt; int ui = 0;
;     if (!S.next(0, cur)) return;
;     f32x4 acc[2][2][4][2];
; #pragma unroll
;     for (int a = 0; a < 2; ++a)
; #pragma unroll
;         for (int b = 0; b < 2; ++b)
; #pragma unroll
;             for (int m = 0; m < 4; ++m)
; #pragma unroll
;                 for (int n = 0; n < 2; ++n) acc[a][b][m][n] = (f32x4){0.f, 0.f, 0.f, 0.f};
;     half8 At[4][2], B0[2][2], B1[2][2];
;     const char* cA = (const char*)g.A + (size_t)cur.pm * tstep; const char* cB = (const char*)g.Bt + (size_t)cur.pn * tstep;
;     S.a_ready(cur);
;     if constexpr (SP2) {
;         PG8_STAGE(PG8_SB(0, 0), cB, voffB); PG8_STAGE(PG8_SB(0, 1), cB + hstep, voffB); PG8_STAGE(PG8_SA(0, 0), cA, voffA); PG8_STAGE(PG8_SA(0, 1), cA + hstep, voffA);
;         if (wr == 1) PG8_BAR;
.LBB0_256:
.LBB0_257:
	s_cmp_lt_i32 s26, 3
	s_cselect_b64 s[0:1], -1, 0
	s_cmp_gt_i32 s27, 2
	s_cselect_b64 s[4:5], -1, 0
	s_and_b64 s[0:1], s[0:1], s[4:5]
	s_andn2_b64 vcc, exec, s[0:1]
	s_cbranch_vccnz .LBB0_338
	s_cmpk_gt_i32 s2, 0xb7f
	v_readfirstlane_b32 s5, v1
	s_cbranch_scc1 .LBB0_274
	s_bitcmp1_b32 s5, 8
	s_cbranch_scc0 .Lprio_g3719
	s_setprio 1
.Lprio_g3719:
	v_lshrrev_b32_e32 v2, 5, v1
	v_lshrrev_b32_e32 v4, 1, v1
	v_and_b32_e32 v2, 4, v2
	v_bfe_u32 v3, v1, 2, 2
	v_and_b32_e32 v13, 24, v4
	v_or3_b32 v2, v2, v3, v13
	v_lshlrev_b32_e32 v3, 4, v1
	v_add_u32_e32 v10, 0x2000, v3
	v_lshrrev_b32_e32 v4, 7, v10
	s_movk_i32 s4, 0xe0
	v_and_b32_e32 v6, 32, v1
	s_add_u32 s0, s24, 0x6564000
	v_and_or_b32 v5, v4, s4, v2
	v_bitop3_b32 v11, v3, v6, 48 bitop3:0x6c
	v_and_b32_e32 v12, 64, v1
	v_bfe_u32 v14, v1, 2, 4
	s_movk_i32 s4, 0xf0
	s_addc_u32 s1, s25, 0
	v_or_b32_e32 v3, v11, v12
	v_and_or_b32 v4, v4, s4, v14
	s_add_u32 s3, s24, 0x44000
	v_lshl_or_b32 v132, v4, 12, v3
	v_lshrrev_b32_e32 v4, 3, v1
	s_movk_i32 s4, 0x60
	s_addc_u32 s14, s25, 0
	v_and_or_b32 v2, v4, s4, v2
	s_movk_i32 s4, 0x70
	s_ashr_i32 s16, s2, 31
	v_lshl_or_b32 v134, v2, 12, v3
	v_and_or_b32 v2, v4, s4, v14
	s_lshr_b32 s4, s16, 29
	s_add_i32 s4, s2, s4
	s_lshr_b32 s10, s5, 6
	s_ashr_i32 s6, s4, 3
	s_and_b32 s4, s4, -8
	s_lshr_b32 s12, s5, 8
	s_lshl_b32 s15, s10, 10
	s_sub_i32 s4, s2, s4
	s_cmp_lt_i32 s4, 0
	s_movk_i32 s17, 0x171
	s_cselect_b32 s7, s17, 0x170
	s_mul_i32 s4, s4, s7
	s_add_i32 s4, s4, s6
	s_mul_hi_i32 s6, s4, 0xb21642c9
	s_add_i32 s6, s6, s4
	s_lshr_b32 s7, s6, 31
	s_ashr_i32 s6, s6, 7
	s_add_i32 s6, s6, s7
	s_lshl_b32 s7, s6, 3
	s_mulk_i32 s6, 0xb8
	s_sub_i32 s6, s4, s6
	s_sext_i32_i16 s4, s6
	s_bfe_u32 s4, s4, 0x3001c
	s_add_i32 s8, s6, s4
	s_sext_i32_i16 s4, s8
	s_and_b32 s8, s8, 0xfff8
	s_sub_i32 s6, s6, s8
	s_sext_i32_i16 s6, s6
	s_lshr_b32 s4, s4, 3
	s_add_i32 s18, s7, s6
	s_ashr_i32 s19, s18, 31
	s_bfe_i64 s[8:9], s[4:5], 0x100000
	s_lshl_b64 s[6:7], s[18:19], 20
	s_lshl_b64 s[8:9], s[8:9], 20
	s_add_u32 s36, s3, s8
	s_addc_u32 s37, s14, s9
	s_add_i32 s19, s15, 0
	s_add_i32 m0, s19, 0x10000
	v_lshl_or_b32 v130, v5, 12, v3
	global_load_lds_dwordx4 v134, s[36:37]
	s_add_i32 m0, s19, 0x12000
	s_add_u32 s8, s36, 0x80000
	global_load_lds_dwordx4 v130, s[36:37]
	s_addc_u32 s9, s37, 0
	s_add_i32 m0, s19, 0x14000
	v_lshl_or_b32 v136, v2, 12, v3
	global_load_lds_dwordx4 v134, s[8:9]
	s_add_i32 m0, s19, 0x16000
	s_add_u32 s34, s0, s6
	s_addc_u32 s35, s1, s7
	s_add_i32 s33, s19, 0x2000
	global_load_lds_dwordx4 v130, s[8:9]
	s_mov_b32 m0, s19
	s_add_u32 s6, s34, 0x80000
	global_load_lds_dwordx4 v136, s[34:35]
	s_mov_b32 m0, s33
	s_addc_u32 s7, s35, 0
	s_add_i32 s40, s19, 0x4000
	global_load_lds_dwordx4 v132, s[34:35]
	s_mov_b32 m0, s40
	s_add_i32 s41, s19, 0x6000
	global_load_lds_dwordx4 v136, s[6:7]
	s_mov_b32 m0, s41
	v_mov_b32_e32 v135, 0
	global_load_lds_dwordx4 v132, s[6:7]
	v_mov_b32_e32 v131, v135
	v_mov_b32_e32 v137, v135
	v_mov_b32_e32 v133, v135
	s_cmp_eq_u32 s12, 1
	s_mov_b32 s42, 0
	v_lshl_add_u64 v[8:9], s[36:37], 0, v[134:135]
	v_lshl_add_u64 v[6:7], s[36:37], 0, v[130:131]
	v_lshl_add_u64 v[2:3], s[34:35], 0, v[136:137]
	s_cselect_b64 s[6:7], -1, 0
	s_cmp_lg_u32 s12, 1
	v_lshl_add_u64 v[4:5], s[34:35], 0, v[132:133]
	s_cbranch_scc1 .LBB0_261
	s_barrier

; #define PG8_STAGE(bufoff, gbase, voff) do { _Pragma("unroll") for (int _i = 0; _i < 2; ++_i) \
;         __builtin_amdgcn_global_load_lds((const unsigned*)((const char*)(gbase) + (voff)[_i]), (LAS unsigned*)(lds + (bufoff) + ldsw + _i * 8192), 16, 0, 0); } while (0)
; #define PG8_LDA(dst, b, h) do { _Pragma("unroll") for (int m = 0; m < 4; ++m) _Pragma("unroll") for (int k = 0; k < 2; ++k) dst[m][k] = *(const LAS half8*)(lds + PG8_SA(b, h) + aoff + m * 2048 + k * 1024); } while (0)
; #define PG8_LDB(dst, b, h) do { _Pragma("unroll") for (int n = 0; n < 2; ++n) _Pragma("unroll") for (int k = 0; k < 2; ++k) dst[n][k] = *(const LAS half8*)(lds + PG8_SB(b, h) + boff + n * 2048 + k * 1024); } while (0)
; #define PG8_WAIT_V(n) asm volatile("s_waitcnt vmcnt(" #n ")" ::: "memory")
; #define PG8_WAIT_L(n) asm volatile("s_waitcnt lgkmcnt(" #n ")" ::: "memory")
; #define PG8_BAR __builtin_amdgcn_s_barrier()
; #define PG8_SCHED __builtin_amdgcn_sched_barrier(0)
; template <bool BF16, class Epi, class Sched, bool ALIGN_EPI = true, bool SP2 = true>
; __device__ __forceinline__ void gemm_phase(LAS unsigned char* lds, const Gemm g, const Sched& S, const Epi& E) {
;     ...
;             PG8_LDB(B0, 0, 0); PG8_LDB(B1, 0, 1); PG8_SCHED; PG8_LDA(At, 0, 0); PG8_STAGE(PG8_SA(1, 1), a1 + hstep, voffA);
;             PG8_WAIT_V(8); PG8_WAIT_L(0); PG8_BAR; PG8_MMA(0, 0, At, B0); PG8_MMA(0, 1, At, B1); PG8_BAR; PG8_SCHED;
;             PG8_LDA(At, 0, 1); PG8_STAGE(PG8_SB(0, 0), b2, voffB); PG8_STAGE(PG8_SB(0, 1), b2 + hstep, voffB); PG8_STAGE(PG8_SA(0, 0), a2, voffA);
.LBB0_267:
	ds_read_b128 v[152:155], v149
	ds_read_b128 v[156:159], v149 offset:1024
	ds_read_b128 v[160:163], v149 offset:2048
	ds_read_b128 v[164:167], v149 offset:3072
	ds_read_b128 v[168:171], v150
	ds_read_b128 v[172:175], v150 offset:1024
	ds_read_b128 v[176:179], v150 offset:2048
	ds_read_b128 v[180:183], v150 offset:3072
	s_add_u32 s36, s34, 0xfff80080
	s_addc_u32 s37, s35, -1
	s_cmp_eq_u32 s54, 28
	s_cselect_b32 s39, s23, s37
	s_cselect_b32 s38, s50, s36
	s_cselect_b32 s37, s21, s53
	s_cselect_b32 s36, s51, s52
	v_lshl_add_u64 v[216:217], s[34:35], 0, v[138:139]
	s_add_i32 m0, s19, 0xc000
	ds_read_b128 v[184:187], v151
	ds_read_b128 v[188:191], v151 offset:1024
	ds_read_b128 v[192:195], v151 offset:2048
	ds_read_b128 v[196:199], v151 offset:3072
	ds_read_b128 v[200:203], v151 offset:4096
	ds_read_b128 v[204:207], v151 offset:5120
	ds_read_b128 v[208:211], v151 offset:6144
	ds_read_b128 v[212:215], v151 offset:7168
	global_load_lds_dwordx4 v[216:217], off
	v_lshl_add_u64 v[216:217], s[34:35], 0, v[140:141]
	s_add_i32 m0, s19, 0xe000
	s_nop 0
	global_load_lds_dwordx4 v[216:217], off
	s_waitcnt vmcnt(8)
	s_waitcnt lgkmcnt(0)
	s_barrier
	s_waitcnt lgkmcnt(0)
	v_mfma_f32_16x16x32_f16 v[126:129], v[152:155], v[184:187], v[126:129]
	v_mfma_f32_16x16x32_f16 v[122:125], v[160:163], v[184:187], v[122:125]
	v_mfma_f32_16x16x32_f16 v[118:121], v[152:155], v[192:195], v[118:121]
	v_mfma_f32_16x16x32_f16 v[114:117], v[160:163], v[192:195], v[114:117]
	v_mfma_f32_16x16x32_f16 v[102:105], v[152:155], v[200:203], v[102:105]
	v_mfma_f32_16x16x32_f16 v[98:101], v[160:163], v[200:203], v[98:101]
	v_mfma_f32_16x16x32_f16 v[86:89], v[152:155], v[208:211], v[86:89]
	v_mfma_f32_16x16x32_f16 v[82:85], v[160:163], v[208:211], v[82:85]
	v_mfma_f32_16x16x32_f16 v[126:129], v[156:159], v[188:191], v[126:129]
	v_mfma_f32_16x16x32_f16 v[122:125], v[164:167], v[188:191], v[122:125]
	v_mfma_f32_16x16x32_f16 v[118:121], v[156:159], v[196:199], v[118:121]
	v_mfma_f32_16x16x32_f16 v[114:117], v[164:167], v[196:199], v[114:117]
	v_mfma_f32_16x16x32_f16 v[102:105], v[156:159], v[204:207], v[102:105]
	v_mfma_f32_16x16x32_f16 v[98:101], v[164:167], v[204:207], v[98:101]
	v_mfma_f32_16x16x32_f16 v[86:89], v[156:159], v[212:215], v[86:89]
	v_mfma_f32_16x16x32_f16 v[82:85], v[164:167], v[212:215], v[82:85]
	v_mfma_f32_16x16x32_f16 v[110:113], v[168:171], v[184:187], v[110:113]
	v_mfma_f32_16x16x32_f16 v[106:109], v[176:179], v[184:187], v[106:109]
	v_mfma_f32_16x16x32_f16 v[94:97], v[168:171], v[192:195], v[94:97]
	v_mfma_f32_16x16x32_f16 v[90:93], v[176:179], v[192:195], v[90:93]
	v_mfma_f32_16x16x32_f16 v[78:81], v[168:171], v[200:203], v[78:81]
	v_mfma_f32_16x16x32_f16 v[74:77], v[176:179], v[200:203], v[74:77]
	v_mfma_f32_16x16x32_f16 v[70:73], v[168:171], v[208:211], v[70:73]
	v_mfma_f32_16x16x32_f16 v[66:69], v[176:179], v[208:211], v[66:69]
	v_mfma_f32_16x16x32_f16 v[110:113], v[172:175], v[188:191], v[110:113]
	v_mfma_f32_16x16x32_f16 v[106:109], v[180:183], v[188:191], v[106:109]
	v_mfma_f32_16x16x32_f16 v[94:97], v[172:175], v[196:199], v[94:97]
	v_mfma_f32_16x16x32_f16 v[90:93], v[180:183], v[196:199], v[90:93]
	v_mfma_f32_16x16x32_f16 v[78:81], v[172:175], v[204:207], v[78:81]
	v_mfma_f32_16x16x32_f16 v[74:77], v[180:183], v[204:207], v[74:77]
	v_mfma_f32_16x16x32_f16 v[70:73], v[172:175], v[212:215], v[70:73]
	v_mfma_f32_16x16x32_f16 v[66:69], v[180:183], v[212:215], v[66:69]
	s_barrier
	s_add_i32 s55, s46, s15
	v_lshl_add_u64 v[216:217], s[36:37], 0, v[134:135]
	s_mov_b32 m0, s55
	ds_read_b128 v[184:187], v151 offset:16384
	ds_read_b128 v[188:191], v151 offset:17408
	ds_read_b128 v[192:195], v151 offset:18432
	ds_read_b128 v[196:199], v151 offset:19456
	ds_read_b128 v[200:203], v151 offset:20480
	ds_read_b128 v[204:207], v151 offset:21504
	ds_read_b128 v[208:211], v151 offset:22528
	ds_read_b128 v[212:215], v151 offset:23552
	global_load_lds_dwordx4 v[216:217], off
	s_add_i32 m0, s55, 0x2000
	s_add_u32 s56, s36, 0x80000
	v_lshl_add_u64 v[218:219], s[36:37], 0, v[130:131]
	s_addc_u32 s57, s37, 0
	s_add_i32 s55, s47, s15
	global_load_lds_dwordx4 v[218:219], off
	v_lshl_add_u64 v[220:221], s[56:57], 0, v[134:135]
	s_mov_b32 m0, s55
	v_lshl_add_u64 v[222:223], s[38:39], 0, v[132:133]
	global_load_lds_dwordx4 v[220:221], off
	v_lshl_add_u64 v[220:221], s[56:57], 0, v[130:131]
	s_add_i32 m0, s55, 0x2000
	s_nop 0
	global_load_lds_dwordx4 v[220:221], off
	v_lshl_add_u64 v[220:221], s[38:39], 0, v[136:137]
	s_mov_b32 m0, s19
	s_nop 0
	global_load_lds_dwordx4 v[220:221], off
	s_mov_b32 m0, s33
	s_nop 0
	global_load_lds_dwordx4 v[222:223], off
	s_waitcnt vmcnt(8)
	s_waitcnt lgkmcnt(0)
	s_barrier
; #define PG8_STAGE(bufoff, gbase, voff) do { _Pragma("unroll") for (int _i = 0; _i < 2; ++_i) \
;         __builtin_amdgcn_global_load_lds((const unsigned*)((const char*)(gbase) + (voff)[_i]), (LAS unsigned*)(lds + (bufoff) + ldsw + _i * 8192), 16, 0, 0); } while (0)
; #define PG8_LDA(dst, b, h) do { _Pragma("unroll") for (int m = 0; m < 4; ++m) _Pragma("unroll") for (int k = 0; k < 2; ++k) dst[m][k] = *(const LAS half8*)(lds + PG8_SA(b, h) + aoff + m * 2048 + k * 1024); } while (0)
; #define PG8_LDB(dst, b, h) do { _Pragma("unroll") for (int n = 0; n < 2; ++n) _Pragma("unroll") for (int k = 0; k < 2; ++k) dst[n][k] = *(const LAS half8*)(lds + PG8_SB(b, h) + boff + n * 2048 + k * 1024); } while (0)
; #define PG8_WAIT_V(n) asm volatile("s_waitcnt vmcnt(" #n ")" ::: "memory")
; #define PG8_WAIT_L(n) asm volatile("s_waitcnt lgkmcnt(" #n ")" ::: "memory")
; #define PG8_BAR __builtin_amdgcn_s_barrier()
; #define PG8_SCHED __builtin_amdgcn_sched_barrier(0)
; template <bool BF16, class Epi, class Sched, bool ALIGN_EPI = true, bool SP2 = true>
; __device__ __forceinline__ void gemm_phase(LAS unsigned char* lds, const Gemm g, const Sched& S, const Epi& E) {
;     ...
;             PG8_WAIT_V(8); PG8_WAIT_L(0); PG8_BAR; PG8_MMA(1, 0, At, B0); PG8_MMA(1, 1, At, B1); PG8_BAR; PG8_SCHED;
;             PG8_LDB(B0, 1, 0); PG8_LDB(B1, 1, 1); PG8_SCHED; PG8_LDA(At, 1, 0); PG8_STAGE(PG8_SA(0, 1), a2 + hstep, voffA);
;             PG8_WAIT_V(8); PG8_WAIT_L(0); PG8_BAR; PG8_MMA(0, 0, At, B0); PG8_MMA(0, 1, At, B1); PG8_BAR; PG8_SCHED;
	s_waitcnt lgkmcnt(0)
	v_mfma_f32_16x16x32_f16 v[62:65], v[152:155], v[184:187], v[62:65]
	v_mfma_f32_16x16x32_f16 v[58:61], v[160:163], v[184:187], v[58:61]
	v_mfma_f32_16x16x32_f16 v[54:57], v[152:155], v[192:195], v[54:57]
	v_mfma_f32_16x16x32_f16 v[50:53], v[160:163], v[192:195], v[50:53]
	v_mfma_f32_16x16x32_f16 v[38:41], v[152:155], v[200:203], v[38:41]
	v_mfma_f32_16x16x32_f16 v[34:37], v[160:163], v[200:203], v[34:37]
	v_mfma_f32_16x16x32_f16 v[22:25], v[152:155], v[208:211], v[22:25]
	v_mfma_f32_16x16x32_f16 v[18:21], v[160:163], v[208:211], v[18:21]
	v_mfma_f32_16x16x32_f16 v[62:65], v[156:159], v[188:191], v[62:65]
	v_mfma_f32_16x16x32_f16 v[58:61], v[164:167], v[188:191], v[58:61]
	v_mfma_f32_16x16x32_f16 v[54:57], v[156:159], v[196:199], v[54:57]
	v_mfma_f32_16x16x32_f16 v[50:53], v[164:167], v[196:199], v[50:53]
	v_mfma_f32_16x16x32_f16 v[38:41], v[156:159], v[204:207], v[38:41]
	v_mfma_f32_16x16x32_f16 v[34:37], v[164:167], v[204:207], v[34:37]
	v_mfma_f32_16x16x32_f16 v[22:25], v[156:159], v[212:215], v[22:25]
	v_mfma_f32_16x16x32_f16 v[18:21], v[164:167], v[212:215], v[18:21]
	v_mfma_f32_16x16x32_f16 v[46:49], v[168:171], v[184:187], v[46:49]
	v_mfma_f32_16x16x32_f16 v[42:45], v[176:179], v[184:187], v[42:45]
	v_mfma_f32_16x16x32_f16 v[30:33], v[168:171], v[192:195], v[30:33]
	v_mfma_f32_16x16x32_f16 v[26:29], v[176:179], v[192:195], v[26:29]
	v_mfma_f32_16x16x32_f16 v[14:17], v[168:171], v[200:203], v[14:17]
	v_mfma_f32_16x16x32_f16 v[10:13], v[176:179], v[200:203], v[10:13]
	v_mfma_f32_16x16x32_f16 v[6:9], v[168:171], v[208:211], v[6:9]
	v_mfma_f32_16x16x32_f16 v[2:5], v[176:179], v[208:211], v[2:5]
	v_mfma_f32_16x16x32_f16 v[46:49], v[172:175], v[188:191], v[46:49]
	v_mfma_f32_16x16x32_f16 v[42:45], v[180:183], v[188:191], v[42:45]
	v_mfma_f32_16x16x32_f16 v[30:33], v[172:175], v[196:199], v[30:33]
	v_mfma_f32_16x16x32_f16 v[26:29], v[180:183], v[196:199], v[26:29]
	v_mfma_f32_16x16x32_f16 v[14:17], v[172:175], v[204:207], v[14:17]
	v_mfma_f32_16x16x32_f16 v[10:13], v[180:183], v[204:207], v[10:13]
	v_mfma_f32_16x16x32_f16 v[6:9], v[172:175], v[212:215], v[6:9]
	v_mfma_f32_16x16x32_f16 v[2:5], v[180:183], v[212:215], v[2:5]
	s_barrier
	s_add_i32 s55, 0, 0x18000
	s_add_i32 s56, 0, 0x1c000
	v_add_u32_e32 v164, s55, v147
	v_add_u32_e32 v180, s56, v147
	ds_read_b128 v[152:155], v164
	ds_read_b128 v[156:159], v164 offset:1024
	ds_read_b128 v[160:163], v164 offset:2048
	ds_read_b128 v[164:167], v164 offset:3072
	ds_read_b128 v[168:171], v180
	ds_read_b128 v[172:175], v180 offset:1024
	ds_read_b128 v[176:179], v180 offset:2048
	ds_read_b128 v[180:183], v180 offset:3072
	s_add_u32 s38, s38, 0x80000
	s_addc_u32 s39, s39, 0
	s_mov_b32 m0, s40
	v_lshl_add_u64 v[224:225], s[38:39], 0, v[136:137]
	ds_read_b128 v[184:187], v151 offset:32768
	ds_read_b128 v[188:191], v151 offset:33792
	ds_read_b128 v[192:195], v151 offset:34816
	ds_read_b128 v[196:199], v151 offset:35840
	ds_read_b128 v[200:203], v151 offset:36864
	ds_read_b128 v[204:207], v151 offset:37888
	ds_read_b128 v[208:211], v151 offset:38912
	ds_read_b128 v[212:215], v151 offset:39936
	global_load_lds_dwordx4 v[224:225], off
	v_lshl_add_u64 v[224:225], s[38:39], 0, v[132:133]
	s_mov_b32 m0, s41
	s_nop 0
	global_load_lds_dwordx4 v[224:225], off
	s_waitcnt vmcnt(8)
	s_waitcnt lgkmcnt(0)
	s_barrier
	s_waitcnt lgkmcnt(0)
	v_mfma_f32_16x16x32_f16 v[126:129], v[152:155], v[184:187], v[126:129]
	v_mfma_f32_16x16x32_f16 v[122:125], v[160:163], v[184:187], v[122:125]
	v_mfma_f32_16x16x32_f16 v[118:121], v[152:155], v[192:195], v[118:121]
	v_mfma_f32_16x16x32_f16 v[114:117], v[160:163], v[192:195], v[114:117]
	v_mfma_f32_16x16x32_f16 v[102:105], v[152:155], v[200:203], v[102:105]
	v_mfma_f32_16x16x32_f16 v[98:101], v[160:163], v[200:203], v[98:101]
	v_mfma_f32_16x16x32_f16 v[86:89], v[152:155], v[208:211], v[86:89]
	v_mfma_f32_16x16x32_f16 v[82:85], v[160:163], v[208:211], v[82:85]
	v_mfma_f32_16x16x32_f16 v[126:129], v[156:159], v[188:191], v[126:129]
	v_mfma_f32_16x16x32_f16 v[122:125], v[164:167], v[188:191], v[122:125]
	v_mfma_f32_16x16x32_f16 v[118:121], v[156:159], v[196:199], v[118:121]
	v_mfma_f32_16x16x32_f16 v[114:117], v[164:167], v[196:199], v[114:117]
	v_mfma_f32_16x16x32_f16 v[102:105], v[156:159], v[204:207], v[102:105]
	v_mfma_f32_16x16x32_f16 v[98:101], v[164:167], v[204:207], v[98:101]
	v_mfma_f32_16x16x32_f16 v[86:89], v[156:159], v[212:215], v[86:89]
	v_mfma_f32_16x16x32_f16 v[82:85], v[164:167], v[212:215], v[82:85]
	v_mfma_f32_16x16x32_f16 v[110:113], v[168:171], v[184:187], v[110:113]
	v_mfma_f32_16x16x32_f16 v[106:109], v[176:179], v[184:187], v[106:109]
	v_mfma_f32_16x16x32_f16 v[94:97], v[168:171], v[192:195], v[94:97]
	v_mfma_f32_16x16x32_f16 v[90:93], v[176:179], v[192:195], v[90:93]
	v_mfma_f32_16x16x32_f16 v[78:81], v[168:171], v[200:203], v[78:81]
	v_mfma_f32_16x16x32_f16 v[74:77], v[176:179], v[200:203], v[74:77]
	v_mfma_f32_16x16x32_f16 v[70:73], v[168:171], v[208:211], v[70:73]
	v_mfma_f32_16x16x32_f16 v[66:69], v[176:179], v[208:211], v[66:69]
	v_mfma_f32_16x16x32_f16 v[110:113], v[172:175], v[188:191], v[110:113]
	v_mfma_f32_16x16x32_f16 v[106:109], v[180:183], v[188:191], v[106:109]
	v_mfma_f32_16x16x32_f16 v[94:97], v[172:175], v[196:199], v[94:97]
	v_mfma_f32_16x16x32_f16 v[90:93], v[180:183], v[196:199], v[90:93]
	v_mfma_f32_16x16x32_f16 v[78:81], v[172:175], v[204:207], v[78:81]
	v_mfma_f32_16x16x32_f16 v[74:77], v[180:183], v[204:207], v[74:77]
	v_mfma_f32_16x16x32_f16 v[70:73], v[172:175], v[212:215], v[70:73]
	v_mfma_f32_16x16x32_f16 v[66:69], v[180:183], v[212:215], v[66:69]
	s_barrier
; #define PG8_STAGE(bufoff, gbase, voff) do { _Pragma("unroll") for (int _i = 0; _i < 2; ++_i) \
;         __builtin_amdgcn_global_load_lds((const unsigned*)((const char*)(gbase) + (voff)[_i]), (LAS unsigned*)(lds + (bufoff) + ldsw + _i * 8192), 16, 0, 0); } while (0)
; #define PG8_LDA(dst, b, h) do { _Pragma("unroll") for (int m = 0; m < 4; ++m) _Pragma("unroll") for (int k = 0; k < 2; ++k) dst[m][k] = *(const LAS half8*)(lds + PG8_SA(b, h) + aoff + m * 2048 + k * 1024); } while (0)
; #define PG8_WAIT_V(n) asm volatile("s_waitcnt vmcnt(" #n ")" ::: "memory")
; template <bool BF16, class Epi, class Sched, bool ALIGN_EPI = true, bool SP2 = true>
; __device__ __forceinline__ void gemm_phase(LAS unsigned char* lds, const Gemm g, const Sched& S, const Epi& E) {
;     ...
;             PG8_LDA(At, 1, 1); PG8_STAGE(PG8_SB(1, 0), b3, voffB); PG8_STAGE(PG8_SB(1, 1), b3 + hstep, voffB); PG8_STAGE(PG8_SA(1, 0), a3, voffA);
;             PG8_WAIT_V(8); PG8_WAIT_L(0); PG8_BAR; PG8_MMA(1, 0, At, B0); PG8_MMA(1, 1, At, B1); PG8_BAR; PG8_SCHED;
;             } else {
;             PG8_LDB(B0, 0, 0); PG8_SCHED; PG8_LDA(At, 0, 0); PG8_STAGE(PG8_SA(1, 1), a1 + hstep, voffA);
;             PG8_WAIT_L(8); PG8_BAR; PG8_WAIT_L(0); PG8_MMA(0, 0, At, B0); PG8_BAR; PG8_SCHED;
;             PG8_LDB(B1, 0, 1); PG8_STAGE(PG8_SB(0, 0), b2, voffB);
;             PG8_BAR; PG8_WAIT_L(0); PG8_MMA(0, 1, At, B1); PG8_BAR;
;             PG8_LDA(At, 0, 1); PG8_STAGE(PG8_SA(0, 0), a2, voffA);
;             PG8_BAR; PG8_WAIT_L(0); PG8_MMA(1, 0, At, B0); PG8_BAR; PG8_SCHED;
;             PG8_STAGE(PG8_SB(0, 1), b2 + hstep, voffB);
;             PG8_WAIT_V(6); PG8_BAR; PG8_MMA(1, 1, At, B1); PG8_BAR;
;             PG8_LDB(B0, 1, 0); PG8_SCHED; PG8_LDA(At, 1, 0); PG8_STAGE(PG8_SA(0, 1), a2 + hstep, voffA);
;             PG8_WAIT_L(8); PG8_BAR; PG8_WAIT_L(0); PG8_MMA(0, 0, At, B0); PG8_BAR; PG8_SCHED;
;             PG8_LDB(B1, 1, 1); PG8_STAGE(PG8_SB(1, 0), b3, voffB);
;             PG8_BAR; PG8_WAIT_L(0); PG8_MMA(0, 1, At, B1); PG8_BAR;
;             PG8_LDA(At, 1, 1); PG8_STAGE(PG8_SA(1, 0), a3, voffA);
;             PG8_BAR; PG8_WAIT_L(0); PG8_MMA(1, 0, At, B0); PG8_BAR; PG8_SCHED;
;             PG8_STAGE(PG8_SB(1, 1), b3 + hstep, voffB);
;             PG8_WAIT_V(6); PG8_BAR; PG8_MMA(1, 1, At, B1); PG8_BAR;
;             }
;         }
;         if constexpr (ALIGN_EPI) { if (wr == 0) PG8_BAR; }
	s_add_i32 s38, s55, s15
	v_lshl_add_u64 v[216:217], v[216:217], 0, s[10:11]
	s_mov_b32 m0, s38
	ds_read_b128 v[184:187], v151 offset:49152
	ds_read_b128 v[188:191], v151 offset:50176
	ds_read_b128 v[192:195], v151 offset:51200
	ds_read_b128 v[196:199], v151 offset:52224
	ds_read_b128 v[200:203], v151 offset:53248
	ds_read_b128 v[204:207], v151 offset:54272
	ds_read_b128 v[208:211], v151 offset:55296
	ds_read_b128 v[212:215], v151 offset:56320
	global_load_lds_dwordx4 v[216:217], off
	s_add_i32 m0, s38, 0x2000
	s_add_u32 s36, s36, 0x80080
	v_lshl_add_u64 v[216:217], v[218:219], 0, s[10:11]
	s_addc_u32 s37, s37, 0
	s_add_i32 s38, s56, s15
	global_load_lds_dwordx4 v[216:217], off
	v_lshl_add_u64 v[216:217], s[36:37], 0, v[134:135]
	s_mov_b32 m0, s38
	s_nop 0
	global_load_lds_dwordx4 v[216:217], off
	v_lshl_add_u64 v[216:217], s[36:37], 0, v[130:131]
	s_add_i32 m0, s38, 0x2000
	s_nop 0
	global_load_lds_dwordx4 v[216:217], off
	v_lshl_add_u64 v[216:217], v[220:221], 0, s[10:11]
	s_mov_b32 m0, s43
	s_nop 0
	global_load_lds_dwordx4 v[216:217], off
	v_lshl_add_u64 v[216:217], v[222:223], 0, s[10:11]
	s_mov_b32 m0, s44
	s_nop 0
	global_load_lds_dwordx4 v[216:217], off
	s_waitcnt vmcnt(8)
	s_waitcnt lgkmcnt(0)
	s_barrier
	s_waitcnt lgkmcnt(0)
	v_mfma_f32_16x16x32_f16 v[62:65], v[152:155], v[184:187], v[62:65]
	v_mfma_f32_16x16x32_f16 v[58:61], v[160:163], v[184:187], v[58:61]
	v_mfma_f32_16x16x32_f16 v[54:57], v[152:155], v[192:195], v[54:57]
	v_mfma_f32_16x16x32_f16 v[50:53], v[160:163], v[192:195], v[50:53]
	v_mfma_f32_16x16x32_f16 v[38:41], v[152:155], v[200:203], v[38:41]
	v_mfma_f32_16x16x32_f16 v[34:37], v[160:163], v[200:203], v[34:37]
	v_mfma_f32_16x16x32_f16 v[22:25], v[152:155], v[208:211], v[22:25]
	v_mfma_f32_16x16x32_f16 v[18:21], v[160:163], v[208:211], v[18:21]
	v_mfma_f32_16x16x32_f16 v[62:65], v[156:159], v[188:191], v[62:65]
	v_mfma_f32_16x16x32_f16 v[58:61], v[164:167], v[188:191], v[58:61]
	v_mfma_f32_16x16x32_f16 v[54:57], v[156:159], v[196:199], v[54:57]
	v_mfma_f32_16x16x32_f16 v[50:53], v[164:167], v[196:199], v[50:53]
	v_mfma_f32_16x16x32_f16 v[38:41], v[156:159], v[204:207], v[38:41]
	v_mfma_f32_16x16x32_f16 v[34:37], v[164:167], v[204:207], v[34:37]
	v_mfma_f32_16x16x32_f16 v[22:25], v[156:159], v[212:215], v[22:25]
	v_mfma_f32_16x16x32_f16 v[18:21], v[164:167], v[212:215], v[18:21]
	v_mfma_f32_16x16x32_f16 v[46:49], v[168:171], v[184:187], v[46:49]
	v_mfma_f32_16x16x32_f16 v[42:45], v[176:179], v[184:187], v[42:45]
	v_mfma_f32_16x16x32_f16 v[30:33], v[168:171], v[192:195], v[30:33]
	v_mfma_f32_16x16x32_f16 v[26:29], v[176:179], v[192:195], v[26:29]
	v_mfma_f32_16x16x32_f16 v[14:17], v[168:171], v[200:203], v[14:17]
	v_mfma_f32_16x16x32_f16 v[10:13], v[176:179], v[200:203], v[10:13]
	v_mfma_f32_16x16x32_f16 v[6:9], v[168:171], v[208:211], v[6:9]
	v_mfma_f32_16x16x32_f16 v[2:5], v[176:179], v[208:211], v[2:5]
	v_mfma_f32_16x16x32_f16 v[46:49], v[172:175], v[188:191], v[46:49]
	v_mfma_f32_16x16x32_f16 v[42:45], v[180:183], v[188:191], v[42:45]
	v_mfma_f32_16x16x32_f16 v[30:33], v[172:175], v[196:199], v[30:33]
	v_mfma_f32_16x16x32_f16 v[26:29], v[180:183], v[196:199], v[26:29]
	v_mfma_f32_16x16x32_f16 v[14:17], v[172:175], v[204:207], v[14:17]
	v_mfma_f32_16x16x32_f16 v[10:13], v[180:183], v[204:207], v[10:13]
	v_mfma_f32_16x16x32_f16 v[6:9], v[172:175], v[212:215], v[6:9]
	v_mfma_f32_16x16x32_f16 v[2:5], v[180:183], v[212:215], v[2:5]
	s_barrier
	s_add_i32 s54, s54, 2
	s_add_u32 s34, s34, 0x100
	s_addc_u32 s35, s35, 0
	s_add_u32 s52, s52, 0x100
	s_addc_u32 s53, s53, 0
	s_cmp_gt_u32 s54, 29
	s_cbranch_scc0 .LBB0_267
	s_and_b64 vcc, exec, s[12:13]
	s_cbranch_vccz .LBB0_270
	s_barrier

; #define LAS __attribute__((address_space(3)))
; __device__ __forceinline__ void attn_fast(const Ptrs& P, LAS unsigned char* lds, int G, int bid) {
;     const int tid = threadIdx.x, lane = tid & 63, w = __builtin_amdgcn_readfirstlane(tid >> 6), fr = lane & 15, fq = lane >> 4, qi = fr >> 2, hh = fr & 3;
;     LAS float* IMP = (LAS float*)(lds + 98304) + w * (8 * 132);
;     LAS unsigned* SELM = (LAS unsigned*)(lds + 132096);
;     const h16* U = (const h16*)(P.ws + WS_U); h16* Y = (h16*)(P.ws + WS_YACC);
;     const float SC = 0.08838834764831845f * 1.4426950408889634f;
;     const int NEGBIG = -(1 << 30);
;     unsigned kl[4]; kl[0] = (unsigned)lane; kl[1] = kl[2] = kl[3] = 0u;
;     const int vz = (4 * fq + (fr >> 2)) & 7;
;     const unsigned vl0 = (unsigned)((4 * fq + (fr >> 2)) * 256 + 8 * (fr & 1) + 16 * ((fr >> 1) & 1));
;     const int nunits = (512 + G - 1) / G;
.LBB0_501:
.LBB0_502:
	s_setprio 0
	s_cmp_lt_i32 s26, 6
	s_cselect_b64 s[0:1], -1, 0
	s_cmp_gt_i32 s27, 5
	s_cselect_b64 s[4:5], -1, 0
	s_and_b64 s[0:1], s[0:1], s[4:5]
	s_andn2_b64 vcc, exec, s[0:1]
	s_cbranch_vccnz .LBB0_694
	s_abs_i32 s1, s95
	v_cvt_f32_u32_e32 v2, s1
	s_sub_i32 s5, 0, s1
	s_add_i32 s3, s95, 0x1ff
	s_xor_b32 s4, s3, s95
	v_rcp_iflag_f32_e32 v2, v2
	s_abs_i32 s3, s3
	s_ashr_i32 s4, s4, 31
	v_readfirstlane_b32 s0, v1
	v_mul_f32_e32 v2, 0x4f7ffffe, v2
	v_cvt_u32_f32_e32 v2, v2
	v_writelane_b32 v243, s68, 0
	s_mov_b32 s65, 0
	v_readfirstlane_b32 s6, v2
	s_mul_i32 s5, s5, s6
	s_mul_hi_u32 s5, s6, s5
	s_add_i32 s6, s6, s5
	s_mul_hi_u32 s5, s3, s6
	s_mul_i32 s6, s5, s1
	s_sub_i32 s3, s3, s6
	s_add_i32 s7, s5, 1
	s_sub_i32 s6, s3, s1
	s_cmp_ge_u32 s3, s1
	s_cselect_b32 s5, s7, s5
	s_cselect_b32 s3, s6, s3
	s_add_i32 s6, s5, 1
	s_cmp_ge_u32 s3, s1
	s_cselect_b32 s1, s6, s5
	v_writelane_b32 v243, s69, 1
	s_xor_b32 s1, s1, s4
	v_writelane_b32 v243, s78, 2
	s_sub_i32 s12, s1, s4
	s_cmp_lt_i32 s12, 1
	v_writelane_b32 v243, s79, 3
	v_writelane_b32 v243, s76, 4
	s_cbranch_scc1 .LBB0_630
	s_lshr_b32 s0, s0, 6
	s_mul_i32 s1, s0, 0x1080
	s_add_i32 s85, s1, 0
	s_add_i32 s66, s85, 0x18000
	s_add_u32 s18, s24, 0xe564000
	s_addc_u32 s19, s25, 0
	s_add_u32 s20, s24, 0x25564000
	s_addc_u32 s21, s25, 0
	s_cmpk_lg_i32 s95, 0x100
	s_cselect_b64 s[14:15], -1, 0
	s_lshl_b32 s3, s2, 5
	s_and_b32 s3, s3, 32
	s_ashr_i32 s4, s2, 3
	s_add_i32 s3, s3, s4
	s_bfe_u32 s4, s2, 0x20001
	v_writelane_b32 v243, s4, 5
	v_bfe_u32 v4, v1, 4, 2
	v_writelane_b32 v243, s3, 6
	s_sub_i32 s3, 0x7f, s3
	s_lshl_b32 s70, s0, 3
	v_bfe_u32 v5, v1, 2, 2
	v_lshlrev_b32_e32 v173, 2, v4
	v_lshlrev_b32_e32 v2, 3, v1
	s_add_u32 s71, s24, 0x6364000
	v_or_b32_e32 v6, v173, v5
	v_and_b32_e32 v7, 24, v2
	v_and_b32_e32 v8, 3, v1
	s_addc_u32 s72, s25, 0
	v_lshl_or_b32 v174, v6, 8, v7
	v_writelane_b32 v243, s3, 7
	v_lshlrev_b32_e32 v9, 7, v8
	s_add_u32 s73, s24, 0x6464000
	v_cmp_eq_u32_e64 s[10:11], 0, v8
	v_lshlrev_b32_e32 v6, 5, v6
	v_mov_b32_e32 v8, 0xe0
	s_movk_i32 s3, 0x60
	s_addc_u32 s74, s25, 0
	s_lshl_b32 s75, s0, 11
	s_movk_i32 s0, 0xe0
	v_bitop3_b32 v180, v6, s3, v8 bitop3:0x6c
	s_movk_i32 s77, 0x80
	s_movk_i32 s3, 0xa0
	s_movk_i32 s78, 0xc0
	v_and_b32_e32 v177, 0xe0, v6
	v_bitop3_b32 v178, v6, 32, v8 bitop3:0x6c
	v_bitop3_b32 v179, v6, 64, v8 bitop3:0x6c
	v_bitop3_b32 v181, v6, s77, v8 bitop3:0x6c
	v_bitop3_b32 v182, v6, s3, v8 bitop3:0x6c
	v_bitop3_b32 v183, v6, s78, v8 bitop3:0x6c
	v_bitop3_b32 v184, v6, s0, v6 bitop3:0xc
	s_movk_i32 s3, 0x210
	v_mov_b32_e32 v6, s1
	v_mad_u32_u24 v6, v5, s3, v6
	v_or_b32_e32 v189, v6, v173
	v_add_u32_e32 v6, 0, v184
	v_lshlrev_b32_e32 v8, 10, v4
	s_movk_i32 s1, 0x4000
	v_add3_u32 v190, v6, v8, s1
	v_add_u32_e32 v6, 0, v183
	v_add3_u32 v192, v6, v8, s1
	v_add_u32_e32 v6, 0, v182
	v_add3_u32 v193, v6, v8, s1
	v_add_u32_e32 v6, 0, v181
	v_add3_u32 v194, v6, v8, s1
	v_add_u32_e32 v6, 0, v180
	v_add3_u32 v195, v6, v8, s1
	v_add_u32_e32 v6, 0, v179
	v_writelane_b32 v243, s96, 8
	v_or_b32_e32 v175, s70, v5
	v_lshlrev_b32_e32 v2, 3, v4
	v_lshlrev_b32_e32 v176, 6, v4
	v_lshl_or_b32 v191, v5, 8, v7
	v_add3_u32 v196, v6, v8, s1
	v_add_u32_e32 v6, 0, v178
	v_lshlrev_b32_e32 v4, 7, v4
	v_lshlrev_b32_e32 v5, 5, v5
	v_writelane_b32 v243, s97, 9
	v_and_b32_e32 v172, 63, v1
	s_add_i32 s76, s75, 0
	v_add3_u32 v197, v6, v8, s1
	v_add_u32_e32 v6, 0, v8
	v_bitop3_b32 v4, v4, s0, v5 bitop3:0xc8
	v_mbcnt_lo_u32_b32 v203, -1, 0
	v_writelane_b32 v243, s12, 10
	v_mov_b32_e32 v3, 0
	v_cmp_eq_u32_e64 s[4:5], 0, v172
	v_or_b32_e32 v185, 64, v172
	s_or_b32 s79, s75, 0x400
	v_lshlrev_b32_e32 v186, 4, v175
	v_or_b32_e32 v187, 0xffffffc0, v172
	v_lshl_add_u32 v188, v172, 2, s66
	s_add_i32 s80, s70, 0x80
	s_add_i32 s81, s75, 0x14400
	s_add_i32 s82, s75, 0x10400
	s_add_i32 s83, s75, 0x14000
	s_add_i32 s84, s75, 0x10000
	v_add3_u32 v198, v6, v4, s1
	s_add_i32 s85, s85, 0x18210
	s_movk_i32 s86, 0x2e00
	v_lshlrev_b32_e32 v166, 1, v2
	v_lshlrev_b32_e32 v199, 1, v9
	s_mov_b64 s[30:31], 0x4000
	s_add_i32 s87, s76, 0x8000
	s_mov_b64 s[34:35], 0x4400
	s_add_i32 s88, s76, 0x8400
	s_mov_b32 s89, 0x3e0293ee
	s_add_i32 s90, s76, 0x4400
	s_add_i32 s91, s76, 0xc000
	s_add_i32 s92, s76, 0xc400
	s_movk_i32 s93, 0x2000
	v_mov_b32_e32 v200, 0x3b8637bd
	v_mov_b32_e32 v201, 0x461c4000
	v_mov_b32_e32 v202, 0xff61b1e6
	v_mbcnt_hi_u32_b32 v204, -1, v203
	v_mov_b32_e32 v205, 0x2e00
	v_mov_b32_e32 v206, 0xf149f2ca
	v_writelane_b32 v243, s14, 11
	s_nop 1
	v_writelane_b32 v243, s15, 12
	v_lshrrev_b32_e32 v4, 4, v172
	v_add_u32_e32 v4, s70, v4
	v_and_b32_e32 v5, 15, v172
	v_mul_u32_u24_e32 v6, 0x2e00, v4
	v_xor_b32_e32 v7, v4, v5
	v_and_b32_e32 v7, 15, v7
	v_lshl_add_u32 v244, v7, 4, v6
	v_lshlrev_b32_e32 v7, 1, v4
	v_and_b32_e32 v7, 14, v7
	v_xor_b32_e32 v7, v7, v5
	v_lshl_add_u32 v245, v7, 4, v6
	v_add_u32_e32 v245, 0x200, v245
	v_add_u32_e32 v4, 4, v4
	v_add_u32_e32 v6, 0xb800, v6
	v_xor_b32_e32 v7, v4, v5
	v_and_b32_e32 v7, 15, v7
	v_lshl_add_u32 v246, v7, 4, v6
	v_lshlrev_b32_e32 v7, 1, v4
	v_and_b32_e32 v7, 14, v7
	v_xor_b32_e32 v7, v7, v5
	v_lshl_add_u32 v247, v7, 4, v6
	v_add_u32_e32 v247, 0x200, v247
	v_lshrrev_b32_e32 v4, 4, v172
	v_add_u32_e32 v4, s70, v4
	v_lshlrev_b32_e32 v6, 8, v4
	v_xor_b32_e32 v7, v4, v5
	v_and_b32_e32 v7, 15, v7
	v_lshl_add_u32 v250, v7, 4, v6
	v_lshlrev_b32_e32 v7, 1, v4
	v_and_b32_e32 v7, 14, v7
	v_xor_b32_e32 v7, v7, v5
	v_lshl_add_u32 v251, v7, 4, v6
	v_add_u32_e32 v4, 4, v4
	v_add_u32_e32 v6, 0x400, v6
	v_xor_b32_e32 v7, v4, v5
	v_and_b32_e32 v7, 15, v7
	v_lshl_add_u32 v252, v7, 4, v6
	v_lshlrev_b32_e32 v7, 1, v4
	v_and_b32_e32 v7, 14, v7
	v_xor_b32_e32 v7, v7, v5
	v_lshl_add_u32 v253, v7, 4, v6
	s_branch .LBB0_506

; #define PHASE_BEGIN(n) if (lo <= (n) && (n) < hi) {
; #define PHASE_END(n) if ((n) + 1 < hi) { if (G != 256) cg::this_grid().sync(); else xcd_barrier(xbar); } }
;     __host__ __device__ bool next(int i, Unit& u) const {
;         const long L = (long)i * G + c; if (L >= nwg) return false;
;         int wgid = (int)L; { const int q = nwg / NXCD, r = nwg % NXCD, xcd = wgid % NXCD, off = wgid / NXCD; wgid = (xcd < r ? xcd * (q + 1) : r * (q + 1) + (xcd - r) * q) + off; }
;         const int nig = WGM * nN, gid = wgid / nig, fm = gid * WGM, gsz = (nM - fm) < WGM ? (nM - fm) : WGM;
;         u.pm = fm + ((wgid % nig) % gsz); u.pn = (wgid % nig) / gsz; return true;
; __global__ void __launch_bounds__(NTHR, 2) mega(Args args) {
;     ...
;     PHASE_BEGIN(7) { pg8::Gemm g{(const h16*)(ws + WS_H), (const h16*)(ws + WS_WOUT), NT, DM, DM}; pg8::StaticOrder S; S.init(NT, DM, G, bid);
;                   pg8::EpiRes<true> E{P.in[0], (h16*)(ws + WS_X1H), mod + 2 * 2048, 12288}; pg8::gemm_phase<true>(lds, g, S, E); } PHASE_END(7)
.LBB0_693:
.LBB0_694:
	s_cmp_lt_i32 s26, 8
	s_cselect_b64 s[0:1], -1, 0
	s_cmp_gt_i32 s27, 7
	s_cselect_b64 s[4:5], -1, 0
	s_and_b64 s[0:1], s[0:1], s[4:5]
	s_andn2_b64 vcc, exec, s[0:1]
	s_cbranch_vccnz .LBB0_783
	s_cmpk_gt_i32 s2, 0x3ff
	v_readfirstlane_b32 s18, v1
	s_cbranch_scc1 .LBB0_719
	s_bitcmp1_b32 s18, 8
	s_cbranch_scc0 .Lprio_g15286
	s_setprio 1
.Lprio_g15286:
	s_ashr_i32 s0, s2, 31
	s_lshr_b32 s1, s0, 29
	s_add_i32 s1, s2, s1
	s_and_b32 s3, s1, -8
	s_sub_i32 s3, s2, s3
	s_cmp_gt_i32 s3, -1
	s_cbranch_scc0 .LBB0_698
	s_lshl_b32 s6, s3, 7
	s_cbranch_execz .LBB0_699
	s_branch .LBB0_700

; #define PG8_STAGE(bufoff, gbase, voff) do { _Pragma("unroll") for (int _i = 0; _i < 2; ++_i) \
;         __builtin_amdgcn_global_load_lds((const unsigned*)((const char*)(gbase) + (voff)[_i]), (LAS unsigned*)(lds + (bufoff) + ldsw + _i * 8192), 16, 0, 0); } while (0)
; #define PG8_LDA(dst, b, h) do { _Pragma("unroll") for (int m = 0; m < 4; ++m) _Pragma("unroll") for (int k = 0; k < 2; ++k) dst[m][k] = *(const LAS half8*)(lds + PG8_SA(b, h) + aoff + m * 2048 + k * 1024); } while (0)
; #define PG8_LDB(dst, b, h) do { _Pragma("unroll") for (int n = 0; n < 2; ++n) _Pragma("unroll") for (int k = 0; k < 2; ++k) dst[n][k] = *(const LAS half8*)(lds + PG8_SB(b, h) + boff + n * 2048 + k * 1024); } while (0)
; #define PG8_WAIT_V(n) asm volatile("s_waitcnt vmcnt(" #n ")" ::: "memory")
; #define PG8_WAIT_L(n) asm volatile("s_waitcnt lgkmcnt(" #n ")" ::: "memory")
; #define PG8_BAR __builtin_amdgcn_s_barrier()
; #define PG8_SCHED __builtin_amdgcn_sched_barrier(0)
; template <bool BF16, class Epi, class Sched, bool ALIGN_EPI = true, bool SP2 = true>
; __device__ __forceinline__ void gemm_phase(LAS unsigned char* lds, const Gemm g, const Sched& S, const Epi& E) {
;     ...
;             PG8_LDB(B0, 0, 0); PG8_LDB(B1, 0, 1); PG8_SCHED; PG8_LDA(At, 0, 0); PG8_STAGE(PG8_SA(1, 1), a1 + hstep, voffA);
;             PG8_WAIT_V(8); PG8_WAIT_L(0); PG8_BAR; PG8_MMA(0, 0, At, B0); PG8_MMA(0, 1, At, B1); PG8_BAR; PG8_SCHED;
;             PG8_LDA(At, 0, 1); PG8_STAGE(PG8_SB(0, 0), b2, voffB); PG8_STAGE(PG8_SB(0, 1), b2 + hstep, voffB); PG8_STAGE(PG8_SA(0, 0), a2, voffA);
.LBB0_712:
	ds_read_b128 v[130:133], v167
	ds_read_b128 v[134:137], v167 offset:1024
	ds_read_b128 v[138:141], v167 offset:2048
	ds_read_b128 v[142:145], v167 offset:3072
	ds_read_b128 v[170:173], v168
	ds_read_b128 v[174:177], v168 offset:1024
	ds_read_b128 v[178:181], v168 offset:2048
	ds_read_b128 v[182:185], v168 offset:3072
	s_add_u32 s46, s44, 0xfff80080
	s_addc_u32 s47, s45, -1
	s_cmp_eq_u32 s64, 28
	s_cselect_b32 s49, s37, s47
	s_cselect_b32 s48, s60, s46
	s_cselect_b32 s47, s35, s63
	s_cselect_b32 s46, s61, s62
	v_lshl_add_u64 v[162:163], s[44:45], 0, v[154:155]
	s_add_i32 m0, s17, 0xc000
	ds_read_b128 v[186:189], v169
	ds_read_b128 v[190:193], v169 offset:1024
	ds_read_b128 v[194:197], v169 offset:2048
	ds_read_b128 v[198:201], v169 offset:3072
	ds_read_b128 v[202:205], v169 offset:4096
	ds_read_b128 v[206:209], v169 offset:5120
	ds_read_b128 v[210:213], v169 offset:6144
	ds_read_b128 v[214:217], v169 offset:7168
	global_load_lds_dwordx4 v[162:163], off
	v_lshl_add_u64 v[162:163], s[44:45], 0, v[156:157]
	s_add_i32 m0, s17, 0xe000
	s_nop 0
	global_load_lds_dwordx4 v[162:163], off
	s_waitcnt vmcnt(8)
	s_waitcnt lgkmcnt(0)
	s_barrier
	s_waitcnt lgkmcnt(0)
	v_mfma_f32_16x16x32_bf16 v[126:129], v[130:133], v[186:189], v[126:129]
	v_mfma_f32_16x16x32_bf16 v[122:125], v[138:141], v[186:189], v[122:125]
	v_mfma_f32_16x16x32_bf16 v[110:113], v[130:133], v[194:197], v[110:113]
	v_mfma_f32_16x16x32_bf16 v[106:109], v[138:141], v[194:197], v[106:109]
	v_mfma_f32_16x16x32_bf16 v[94:97], v[130:133], v[202:205], v[94:97]
	v_mfma_f32_16x16x32_bf16 v[90:93], v[138:141], v[202:205], v[90:93]
	v_mfma_f32_16x16x32_bf16 v[78:81], v[130:133], v[210:213], v[78:81]
	v_mfma_f32_16x16x32_bf16 v[74:77], v[138:141], v[210:213], v[74:77]
	v_mfma_f32_16x16x32_bf16 v[126:129], v[134:137], v[190:193], v[126:129]
	v_mfma_f32_16x16x32_bf16 v[122:125], v[142:145], v[190:193], v[122:125]
	v_mfma_f32_16x16x32_bf16 v[110:113], v[134:137], v[198:201], v[110:113]
	v_mfma_f32_16x16x32_bf16 v[106:109], v[142:145], v[198:201], v[106:109]
	v_mfma_f32_16x16x32_bf16 v[94:97], v[134:137], v[206:209], v[94:97]
	v_mfma_f32_16x16x32_bf16 v[90:93], v[142:145], v[206:209], v[90:93]
	v_mfma_f32_16x16x32_bf16 v[78:81], v[134:137], v[214:217], v[78:81]
	v_mfma_f32_16x16x32_bf16 v[74:77], v[142:145], v[214:217], v[74:77]
	v_mfma_f32_16x16x32_bf16 v[118:121], v[170:173], v[186:189], v[118:121]
	v_mfma_f32_16x16x32_bf16 v[114:117], v[178:181], v[186:189], v[114:117]
	v_mfma_f32_16x16x32_bf16 v[102:105], v[170:173], v[194:197], v[102:105]
	v_mfma_f32_16x16x32_bf16 v[98:101], v[178:181], v[194:197], v[98:101]
	v_mfma_f32_16x16x32_bf16 v[86:89], v[170:173], v[202:205], v[86:89]
	v_mfma_f32_16x16x32_bf16 v[82:85], v[178:181], v[202:205], v[82:85]
	v_mfma_f32_16x16x32_bf16 v[70:73], v[170:173], v[210:213], v[70:73]
	v_mfma_f32_16x16x32_bf16 v[66:69], v[178:181], v[210:213], v[66:69]
	v_mfma_f32_16x16x32_bf16 v[118:121], v[174:177], v[190:193], v[118:121]
	v_mfma_f32_16x16x32_bf16 v[114:117], v[182:185], v[190:193], v[114:117]
	v_mfma_f32_16x16x32_bf16 v[102:105], v[174:177], v[198:201], v[102:105]
	v_mfma_f32_16x16x32_bf16 v[98:101], v[182:185], v[198:201], v[98:101]
	v_mfma_f32_16x16x32_bf16 v[86:89], v[174:177], v[206:209], v[86:89]
	v_mfma_f32_16x16x32_bf16 v[82:85], v[182:185], v[206:209], v[82:85]
	v_mfma_f32_16x16x32_bf16 v[70:73], v[174:177], v[214:217], v[70:73]
	v_mfma_f32_16x16x32_bf16 v[66:69], v[182:185], v[214:217], v[66:69]
	s_barrier
	s_add_i32 s65, s57, s16
	v_lshl_add_u64 v[162:163], s[46:47], 0, v[148:149]
	s_mov_b32 m0, s65
	ds_read_b128 v[186:189], v169 offset:16384
	ds_read_b128 v[190:193], v169 offset:17408
	ds_read_b128 v[194:197], v169 offset:18432
	ds_read_b128 v[198:201], v169 offset:19456
	ds_read_b128 v[202:205], v169 offset:20480
	ds_read_b128 v[206:209], v169 offset:21504
	ds_read_b128 v[210:213], v169 offset:22528
	ds_read_b128 v[214:217], v169 offset:23552
	global_load_lds_dwordx4 v[162:163], off
	s_add_i32 m0, s65, 0x2000
	s_add_u32 s66, s46, 0x80000
	v_lshl_add_u64 v[218:219], s[46:47], 0, v[152:153]
	s_addc_u32 s67, s47, 0
	s_add_i32 s65, s58, s16
	global_load_lds_dwordx4 v[218:219], off
	v_lshl_add_u64 v[220:221], s[66:67], 0, v[148:149]
	s_mov_b32 m0, s65
	v_lshl_add_u64 v[222:223], s[48:49], 0, v[150:151]
	global_load_lds_dwordx4 v[220:221], off
	v_lshl_add_u64 v[220:221], s[66:67], 0, v[152:153]
	s_add_i32 m0, s65, 0x2000
	s_nop 0
	global_load_lds_dwordx4 v[220:221], off
	v_lshl_add_u64 v[220:221], s[48:49], 0, v[146:147]
	s_mov_b32 m0, s17
	s_nop 0
	global_load_lds_dwordx4 v[220:221], off
	s_mov_b32 m0, s33
	s_nop 0
	global_load_lds_dwordx4 v[222:223], off
	s_waitcnt vmcnt(8)
	s_waitcnt lgkmcnt(0)
	s_barrier
; #define PG8_STAGE(bufoff, gbase, voff) do { _Pragma("unroll") for (int _i = 0; _i < 2; ++_i) \
;         __builtin_amdgcn_global_load_lds((const unsigned*)((const char*)(gbase) + (voff)[_i]), (LAS unsigned*)(lds + (bufoff) + ldsw + _i * 8192), 16, 0, 0); } while (0)
; #define PG8_LDA(dst, b, h) do { _Pragma("unroll") for (int m = 0; m < 4; ++m) _Pragma("unroll") for (int k = 0; k < 2; ++k) dst[m][k] = *(const LAS half8*)(lds + PG8_SA(b, h) + aoff + m * 2048 + k * 1024); } while (0)
; #define PG8_LDB(dst, b, h) do { _Pragma("unroll") for (int n = 0; n < 2; ++n) _Pragma("unroll") for (int k = 0; k < 2; ++k) dst[n][k] = *(const LAS half8*)(lds + PG8_SB(b, h) + boff + n * 2048 + k * 1024); } while (0)
; #define PG8_WAIT_V(n) asm volatile("s_waitcnt vmcnt(" #n ")" ::: "memory")
; #define PG8_WAIT_L(n) asm volatile("s_waitcnt lgkmcnt(" #n ")" ::: "memory")
; #define PG8_BAR __builtin_amdgcn_s_barrier()
; #define PG8_SCHED __builtin_amdgcn_sched_barrier(0)
; template <bool BF16, class Epi, class Sched, bool ALIGN_EPI = true, bool SP2 = true>
; __device__ __forceinline__ void gemm_phase(LAS unsigned char* lds, const Gemm g, const Sched& S, const Epi& E) {
;     ...
;             PG8_WAIT_V(8); PG8_WAIT_L(0); PG8_BAR; PG8_MMA(1, 0, At, B0); PG8_MMA(1, 1, At, B1); PG8_BAR; PG8_SCHED;
;             PG8_LDB(B0, 1, 0); PG8_LDB(B1, 1, 1); PG8_SCHED; PG8_LDA(At, 1, 0); PG8_STAGE(PG8_SA(0, 1), a2 + hstep, voffA);
;             PG8_WAIT_V(8); PG8_WAIT_L(0); PG8_BAR; PG8_MMA(0, 0, At, B0); PG8_MMA(0, 1, At, B1); PG8_BAR; PG8_SCHED;
	s_waitcnt lgkmcnt(0)
	v_mfma_f32_16x16x32_bf16 v[62:65], v[130:133], v[186:189], v[62:65]
	v_mfma_f32_16x16x32_bf16 v[58:61], v[138:141], v[186:189], v[58:61]
	v_mfma_f32_16x16x32_bf16 v[46:49], v[130:133], v[194:197], v[46:49]
	v_mfma_f32_16x16x32_bf16 v[42:45], v[138:141], v[194:197], v[42:45]
	v_mfma_f32_16x16x32_bf16 v[30:33], v[130:133], v[202:205], v[30:33]
	v_mfma_f32_16x16x32_bf16 v[26:29], v[138:141], v[202:205], v[26:29]
	v_mfma_f32_16x16x32_bf16 v[14:17], v[130:133], v[210:213], v[14:17]
	v_mfma_f32_16x16x32_bf16 v[10:13], v[138:141], v[210:213], v[10:13]
	v_mfma_f32_16x16x32_bf16 v[62:65], v[134:137], v[190:193], v[62:65]
	v_mfma_f32_16x16x32_bf16 v[58:61], v[142:145], v[190:193], v[58:61]
	v_mfma_f32_16x16x32_bf16 v[46:49], v[134:137], v[198:201], v[46:49]
	v_mfma_f32_16x16x32_bf16 v[42:45], v[142:145], v[198:201], v[42:45]
	v_mfma_f32_16x16x32_bf16 v[30:33], v[134:137], v[206:209], v[30:33]
	v_mfma_f32_16x16x32_bf16 v[26:29], v[142:145], v[206:209], v[26:29]
	v_mfma_f32_16x16x32_bf16 v[14:17], v[134:137], v[214:217], v[14:17]
	v_mfma_f32_16x16x32_bf16 v[10:13], v[142:145], v[214:217], v[10:13]
	v_mfma_f32_16x16x32_bf16 v[54:57], v[170:173], v[186:189], v[54:57]
	v_mfma_f32_16x16x32_bf16 v[50:53], v[178:181], v[186:189], v[50:53]
	v_mfma_f32_16x16x32_bf16 v[38:41], v[170:173], v[194:197], v[38:41]
	v_mfma_f32_16x16x32_bf16 v[34:37], v[178:181], v[194:197], v[34:37]
	v_mfma_f32_16x16x32_bf16 v[22:25], v[170:173], v[202:205], v[22:25]
	v_mfma_f32_16x16x32_bf16 v[18:21], v[178:181], v[202:205], v[18:21]
	v_mfma_f32_16x16x32_bf16 v[6:9], v[170:173], v[210:213], v[6:9]
	v_mfma_f32_16x16x32_bf16 v[2:5], v[178:181], v[210:213], v[2:5]
	v_mfma_f32_16x16x32_bf16 v[54:57], v[174:177], v[190:193], v[54:57]
	v_mfma_f32_16x16x32_bf16 v[50:53], v[182:185], v[190:193], v[50:53]
	v_mfma_f32_16x16x32_bf16 v[38:41], v[174:177], v[198:201], v[38:41]
	v_mfma_f32_16x16x32_bf16 v[34:37], v[182:185], v[198:201], v[34:37]
	v_mfma_f32_16x16x32_bf16 v[22:25], v[174:177], v[206:209], v[22:25]
	v_mfma_f32_16x16x32_bf16 v[18:21], v[182:185], v[206:209], v[18:21]
	v_mfma_f32_16x16x32_bf16 v[6:9], v[174:177], v[214:217], v[6:9]
	v_mfma_f32_16x16x32_bf16 v[2:5], v[182:185], v[214:217], v[2:5]
	s_barrier
	s_add_i32 s65, 0, 0x18000
	s_add_i32 s66, 0, 0x1c000
	v_add_u32_e32 v142, s65, v165
	v_add_u32_e32 v182, s66, v165
	ds_read_b128 v[130:133], v142
	ds_read_b128 v[134:137], v142 offset:1024
	ds_read_b128 v[138:141], v142 offset:2048
	ds_read_b128 v[142:145], v142 offset:3072
	ds_read_b128 v[170:173], v182
	ds_read_b128 v[174:177], v182 offset:1024
	ds_read_b128 v[178:181], v182 offset:2048
	ds_read_b128 v[182:185], v182 offset:3072
	s_add_u32 s48, s48, 0x80000
	s_addc_u32 s49, s49, 0
	s_mov_b32 m0, s43
	v_lshl_add_u64 v[224:225], s[48:49], 0, v[146:147]
	ds_read_b128 v[186:189], v169 offset:32768
	ds_read_b128 v[190:193], v169 offset:33792
	ds_read_b128 v[194:197], v169 offset:34816
	ds_read_b128 v[198:201], v169 offset:35840
	ds_read_b128 v[202:205], v169 offset:36864
	ds_read_b128 v[206:209], v169 offset:37888
	ds_read_b128 v[210:213], v169 offset:38912
	ds_read_b128 v[214:217], v169 offset:39936
	global_load_lds_dwordx4 v[224:225], off
	v_lshl_add_u64 v[224:225], s[48:49], 0, v[150:151]
	s_mov_b32 m0, s50
	s_nop 0
	global_load_lds_dwordx4 v[224:225], off
	s_waitcnt vmcnt(8)
	s_waitcnt lgkmcnt(0)
	s_barrier
	s_waitcnt lgkmcnt(0)
	v_mfma_f32_16x16x32_bf16 v[126:129], v[130:133], v[186:189], v[126:129]
	v_mfma_f32_16x16x32_bf16 v[122:125], v[138:141], v[186:189], v[122:125]
	v_mfma_f32_16x16x32_bf16 v[110:113], v[130:133], v[194:197], v[110:113]
	v_mfma_f32_16x16x32_bf16 v[106:109], v[138:141], v[194:197], v[106:109]
	v_mfma_f32_16x16x32_bf16 v[94:97], v[130:133], v[202:205], v[94:97]
	v_mfma_f32_16x16x32_bf16 v[90:93], v[138:141], v[202:205], v[90:93]
	v_mfma_f32_16x16x32_bf16 v[78:81], v[130:133], v[210:213], v[78:81]
	v_mfma_f32_16x16x32_bf16 v[74:77], v[138:141], v[210:213], v[74:77]
	v_mfma_f32_16x16x32_bf16 v[126:129], v[134:137], v[190:193], v[126:129]
	v_mfma_f32_16x16x32_bf16 v[122:125], v[142:145], v[190:193], v[122:125]
	v_mfma_f32_16x16x32_bf16 v[110:113], v[134:137], v[198:201], v[110:113]
	v_mfma_f32_16x16x32_bf16 v[106:109], v[142:145], v[198:201], v[106:109]
	v_mfma_f32_16x16x32_bf16 v[94:97], v[134:137], v[206:209], v[94:97]
	v_mfma_f32_16x16x32_bf16 v[90:93], v[142:145], v[206:209], v[90:93]
	v_mfma_f32_16x16x32_bf16 v[78:81], v[134:137], v[214:217], v[78:81]
	v_mfma_f32_16x16x32_bf16 v[74:77], v[142:145], v[214:217], v[74:77]
	v_mfma_f32_16x16x32_bf16 v[118:121], v[170:173], v[186:189], v[118:121]
	v_mfma_f32_16x16x32_bf16 v[114:117], v[178:181], v[186:189], v[114:117]
	v_mfma_f32_16x16x32_bf16 v[102:105], v[170:173], v[194:197], v[102:105]
	v_mfma_f32_16x16x32_bf16 v[98:101], v[178:181], v[194:197], v[98:101]
	v_mfma_f32_16x16x32_bf16 v[86:89], v[170:173], v[202:205], v[86:89]
	v_mfma_f32_16x16x32_bf16 v[82:85], v[178:181], v[202:205], v[82:85]
	v_mfma_f32_16x16x32_bf16 v[70:73], v[170:173], v[210:213], v[70:73]
	v_mfma_f32_16x16x32_bf16 v[66:69], v[178:181], v[210:213], v[66:69]
	v_mfma_f32_16x16x32_bf16 v[118:121], v[174:177], v[190:193], v[118:121]
	v_mfma_f32_16x16x32_bf16 v[114:117], v[182:185], v[190:193], v[114:117]
	v_mfma_f32_16x16x32_bf16 v[102:105], v[174:177], v[198:201], v[102:105]
	v_mfma_f32_16x16x32_bf16 v[98:101], v[182:185], v[198:201], v[98:101]
	v_mfma_f32_16x16x32_bf16 v[86:89], v[174:177], v[206:209], v[86:89]
	v_mfma_f32_16x16x32_bf16 v[82:85], v[182:185], v[206:209], v[82:85]
	v_mfma_f32_16x16x32_bf16 v[70:73], v[174:177], v[214:217], v[70:73]
	v_mfma_f32_16x16x32_bf16 v[66:69], v[182:185], v[214:217], v[66:69]
	s_barrier
; #define PG8_STAGE(bufoff, gbase, voff) do { _Pragma("unroll") for (int _i = 0; _i < 2; ++_i) \
;         __builtin_amdgcn_global_load_lds((const unsigned*)((const char*)(gbase) + (voff)[_i]), (LAS unsigned*)(lds + (bufoff) + ldsw + _i * 8192), 16, 0, 0); } while (0)
; #define PG8_LDA(dst, b, h) do { _Pragma("unroll") for (int m = 0; m < 4; ++m) _Pragma("unroll") for (int k = 0; k < 2; ++k) dst[m][k] = *(const LAS half8*)(lds + PG8_SA(b, h) + aoff + m * 2048 + k * 1024); } while (0)
; #define PG8_WAIT_V(n) asm volatile("s_waitcnt vmcnt(" #n ")" ::: "memory")
; template <bool BF16, class Epi, class Sched, bool ALIGN_EPI = true, bool SP2 = true>
; __device__ __forceinline__ void gemm_phase(LAS unsigned char* lds, const Gemm g, const Sched& S, const Epi& E) {
;     ...
;             PG8_LDA(At, 1, 1); PG8_STAGE(PG8_SB(1, 0), b3, voffB); PG8_STAGE(PG8_SB(1, 1), b3 + hstep, voffB); PG8_STAGE(PG8_SA(1, 0), a3, voffA);
;             PG8_WAIT_V(8); PG8_WAIT_L(0); PG8_BAR; PG8_MMA(1, 0, At, B0); PG8_MMA(1, 1, At, B1); PG8_BAR; PG8_SCHED;
;             } else {
;             PG8_LDB(B0, 0, 0); PG8_SCHED; PG8_LDA(At, 0, 0); PG8_STAGE(PG8_SA(1, 1), a1 + hstep, voffA);
;             PG8_WAIT_L(8); PG8_BAR; PG8_WAIT_L(0); PG8_MMA(0, 0, At, B0); PG8_BAR; PG8_SCHED;
;             PG8_LDB(B1, 0, 1); PG8_STAGE(PG8_SB(0, 0), b2, voffB);
;             PG8_BAR; PG8_WAIT_L(0); PG8_MMA(0, 1, At, B1); PG8_BAR;
;             PG8_LDA(At, 0, 1); PG8_STAGE(PG8_SA(0, 0), a2, voffA);
;             PG8_BAR; PG8_WAIT_L(0); PG8_MMA(1, 0, At, B0); PG8_BAR; PG8_SCHED;
;             PG8_STAGE(PG8_SB(0, 1), b2 + hstep, voffB);
;             PG8_WAIT_V(6); PG8_BAR; PG8_MMA(1, 1, At, B1); PG8_BAR;
;             PG8_LDB(B0, 1, 0); PG8_SCHED; PG8_LDA(At, 1, 0); PG8_STAGE(PG8_SA(0, 1), a2 + hstep, voffA);
;             PG8_WAIT_L(8); PG8_BAR; PG8_WAIT_L(0); PG8_MMA(0, 0, At, B0); PG8_BAR; PG8_SCHED;
;             PG8_LDB(B1, 1, 1); PG8_STAGE(PG8_SB(1, 0), b3, voffB);
;             PG8_BAR; PG8_WAIT_L(0); PG8_MMA(0, 1, At, B1); PG8_BAR;
;             PG8_LDA(At, 1, 1); PG8_STAGE(PG8_SA(1, 0), a3, voffA);
;             PG8_BAR; PG8_WAIT_L(0); PG8_MMA(1, 0, At, B0); PG8_BAR; PG8_SCHED;
;             PG8_STAGE(PG8_SB(1, 1), b3 + hstep, voffB);
;             PG8_WAIT_V(6); PG8_BAR; PG8_MMA(1, 1, At, B1); PG8_BAR;
;             }
;         }
;         if constexpr (ALIGN_EPI) { if (wr == 0) PG8_BAR; }
	s_add_i32 s48, s65, s16
	v_lshl_add_u64 v[162:163], v[162:163], 0, s[12:13]
	s_mov_b32 m0, s48
	ds_read_b128 v[186:189], v169 offset:49152
	ds_read_b128 v[190:193], v169 offset:50176
	ds_read_b128 v[194:197], v169 offset:51200
	ds_read_b128 v[198:201], v169 offset:52224
	ds_read_b128 v[202:205], v169 offset:53248
	ds_read_b128 v[206:209], v169 offset:54272
	ds_read_b128 v[210:213], v169 offset:55296
	ds_read_b128 v[214:217], v169 offset:56320
	global_load_lds_dwordx4 v[162:163], off
	s_add_i32 m0, s48, 0x2000
	s_add_u32 s46, s46, 0x80080
	v_lshl_add_u64 v[162:163], v[218:219], 0, s[12:13]
	s_addc_u32 s47, s47, 0
	s_add_i32 s48, s66, s16
	global_load_lds_dwordx4 v[162:163], off
	v_lshl_add_u64 v[162:163], s[46:47], 0, v[148:149]
	s_mov_b32 m0, s48
	s_nop 0
	global_load_lds_dwordx4 v[162:163], off
	v_lshl_add_u64 v[162:163], s[46:47], 0, v[152:153]
	s_add_i32 m0, s48, 0x2000
	s_nop 0
	global_load_lds_dwordx4 v[162:163], off
	v_lshl_add_u64 v[162:163], v[220:221], 0, s[12:13]
	s_mov_b32 m0, s54
	s_nop 0
	global_load_lds_dwordx4 v[162:163], off
	v_lshl_add_u64 v[162:163], v[222:223], 0, s[12:13]
	s_mov_b32 m0, s55
	s_nop 0
	global_load_lds_dwordx4 v[162:163], off
	s_waitcnt vmcnt(8)
	s_waitcnt lgkmcnt(0)
	s_barrier
	s_waitcnt lgkmcnt(0)
	v_mfma_f32_16x16x32_bf16 v[62:65], v[130:133], v[186:189], v[62:65]
	v_mfma_f32_16x16x32_bf16 v[58:61], v[138:141], v[186:189], v[58:61]
	v_mfma_f32_16x16x32_bf16 v[46:49], v[130:133], v[194:197], v[46:49]
	v_mfma_f32_16x16x32_bf16 v[42:45], v[138:141], v[194:197], v[42:45]
	v_mfma_f32_16x16x32_bf16 v[30:33], v[130:133], v[202:205], v[30:33]
	v_mfma_f32_16x16x32_bf16 v[26:29], v[138:141], v[202:205], v[26:29]
	v_mfma_f32_16x16x32_bf16 v[14:17], v[130:133], v[210:213], v[14:17]
	v_mfma_f32_16x16x32_bf16 v[10:13], v[138:141], v[210:213], v[10:13]
	v_mfma_f32_16x16x32_bf16 v[62:65], v[134:137], v[190:193], v[62:65]
	v_mfma_f32_16x16x32_bf16 v[58:61], v[142:145], v[190:193], v[58:61]
	v_mfma_f32_16x16x32_bf16 v[46:49], v[134:137], v[198:201], v[46:49]
	v_mfma_f32_16x16x32_bf16 v[42:45], v[142:145], v[198:201], v[42:45]
	v_mfma_f32_16x16x32_bf16 v[30:33], v[134:137], v[206:209], v[30:33]
	v_mfma_f32_16x16x32_bf16 v[26:29], v[142:145], v[206:209], v[26:29]
	v_mfma_f32_16x16x32_bf16 v[14:17], v[134:137], v[214:217], v[14:17]
	v_mfma_f32_16x16x32_bf16 v[10:13], v[142:145], v[214:217], v[10:13]
	v_mfma_f32_16x16x32_bf16 v[54:57], v[170:173], v[186:189], v[54:57]
	v_mfma_f32_16x16x32_bf16 v[50:53], v[178:181], v[186:189], v[50:53]
	v_mfma_f32_16x16x32_bf16 v[38:41], v[170:173], v[194:197], v[38:41]
	v_mfma_f32_16x16x32_bf16 v[34:37], v[178:181], v[194:197], v[34:37]
	v_mfma_f32_16x16x32_bf16 v[22:25], v[170:173], v[202:205], v[22:25]
	v_mfma_f32_16x16x32_bf16 v[18:21], v[178:181], v[202:205], v[18:21]
	v_mfma_f32_16x16x32_bf16 v[6:9], v[170:173], v[210:213], v[6:9]
	v_mfma_f32_16x16x32_bf16 v[2:5], v[178:181], v[210:213], v[2:5]
	v_mfma_f32_16x16x32_bf16 v[54:57], v[174:177], v[190:193], v[54:57]
	v_mfma_f32_16x16x32_bf16 v[50:53], v[182:185], v[190:193], v[50:53]
	v_mfma_f32_16x16x32_bf16 v[38:41], v[174:177], v[198:201], v[38:41]
	v_mfma_f32_16x16x32_bf16 v[34:37], v[182:185], v[198:201], v[34:37]
	v_mfma_f32_16x16x32_bf16 v[22:25], v[174:177], v[206:209], v[22:25]
	v_mfma_f32_16x16x32_bf16 v[18:21], v[182:185], v[206:209], v[18:21]
	v_mfma_f32_16x16x32_bf16 v[6:9], v[174:177], v[214:217], v[6:9]
	v_mfma_f32_16x16x32_bf16 v[2:5], v[182:185], v[214:217], v[2:5]
	s_barrier
	s_add_i32 s64, s64, 2
	s_add_u32 s44, s44, 0x100
	s_addc_u32 s45, s45, 0
	s_add_u32 s62, s62, 0x100
	s_addc_u32 s63, s63, 0
	s_cmp_gt_u32 s64, 29
	s_cbranch_scc0 .LBB0_712
	s_and_b64 vcc, exec, s[18:19]
	s_cbranch_vccz .LBB0_715
	s_barrier

; #define PHASE_BEGIN(n) if (lo <= (n) && (n) < hi) {
; #define PHASE_END(n) if ((n) + 1 < hi) { if (G != 256) cg::this_grid().sync(); else xcd_barrier(xbar); } }
;     __host__ __device__ bool next(int i, Unit& u) const {
;         const long L = (long)i * G + c; if (L >= nwg) return false;
;         int wgid = (int)L; { const int q = nwg / NXCD, r = nwg % NXCD, xcd = wgid % NXCD, off = wgid / NXCD; wgid = (xcd < r ? xcd * (q + 1) : r * (q + 1) + (xcd - r) * q) + off; }
;         const int nig = WGM * nN, gid = wgid / nig, fm = gid * WGM, gsz = (nM - fm) < WGM ? (nM - fm) : WGM;
;         u.pm = fm + ((wgid % nig) % gsz); u.pn = (wgid % nig) / gsz; return true;
; __global__ void __launch_bounds__(NTHR, 2) mega(Args args) {
;     ...
;     PHASE_BEGIN(9) { pg8::Gemm g{(const h16*)(ws + WS_H), (const h16*)(ws + WS_W1), NT, DFF, DM}; pg8::StaticOrder S; S.init(NT, DFF, G, bid);
;                   pg8::EpiF16<1, true> E{(h16*)(ws + WS_HID), DFF}; pg8::gemm_phase<true>(lds, g, S, E); } PHASE_END(9)
.LBB0_850:
.LBB0_851:
	s_cmp_lt_i32 s26, 10
	s_cselect_b64 s[0:1], -1, 0
	s_cmp_gt_i32 s27, 9
	s_cselect_b64 s[4:5], -1, 0
	s_and_b64 s[0:1], s[0:1], s[4:5]
	s_andn2_b64 vcc, exec, s[0:1]
	s_cbranch_vccnz .LBB0_940
	s_cmpk_gt_i32 s2, 0xfff
	v_readfirstlane_b32 s12, v1
	s_cbranch_scc1 .LBB0_876
	s_bitcmp1_b32 s12, 8
	s_cbranch_scc0 .Lprio_g17949
	s_setprio 1
.Lprio_g17949:
	s_ashr_i32 s0, s2, 31
	s_lshr_b32 s1, s0, 29
	s_add_i32 s1, s2, s1
	s_and_b32 s3, s1, -8
	s_sub_i32 s3, s2, s3
	s_cmp_gt_i32 s3, -1
	s_cbranch_scc0 .LBB0_855
	s_lshl_b32 s6, s3, 9
	s_cbranch_execz .LBB0_856
	s_branch .LBB0_857

; #define PG8_STAGE(bufoff, gbase, voff) do { _Pragma("unroll") for (int _i = 0; _i < 2; ++_i) \
;         __builtin_amdgcn_global_load_lds((const unsigned*)((const char*)(gbase) + (voff)[_i]), (LAS unsigned*)(lds + (bufoff) + ldsw + _i * 8192), 16, 0, 0); } while (0)
; #define PG8_LDA(dst, b, h) do { _Pragma("unroll") for (int m = 0; m < 4; ++m) _Pragma("unroll") for (int k = 0; k < 2; ++k) dst[m][k] = *(const LAS half8*)(lds + PG8_SA(b, h) + aoff + m * 2048 + k * 1024); } while (0)
; #define PG8_LDB(dst, b, h) do { _Pragma("unroll") for (int n = 0; n < 2; ++n) _Pragma("unroll") for (int k = 0; k < 2; ++k) dst[n][k] = *(const LAS half8*)(lds + PG8_SB(b, h) + boff + n * 2048 + k * 1024); } while (0)
; #define PG8_WAIT_V(n) asm volatile("s_waitcnt vmcnt(" #n ")" ::: "memory")
; #define PG8_WAIT_L(n) asm volatile("s_waitcnt lgkmcnt(" #n ")" ::: "memory")
; #define PG8_BAR __builtin_amdgcn_s_barrier()
; #define PG8_SCHED __builtin_amdgcn_sched_barrier(0)
; template <bool BF16, class Epi, class Sched, bool ALIGN_EPI = true, bool SP2 = true>
; __device__ __forceinline__ void gemm_phase(LAS unsigned char* lds, const Gemm g, const Sched& S, const Epi& E) {
;     ...
;             PG8_LDB(B0, 0, 0); PG8_LDB(B1, 0, 1); PG8_SCHED; PG8_LDA(At, 0, 0); PG8_STAGE(PG8_SA(1, 1), a1 + hstep, voffA);
;             PG8_WAIT_V(8); PG8_WAIT_L(0); PG8_BAR; PG8_MMA(0, 0, At, B0); PG8_MMA(0, 1, At, B1); PG8_BAR; PG8_SCHED;
;             PG8_LDA(At, 0, 1); PG8_STAGE(PG8_SB(0, 0), b2, voffB); PG8_STAGE(PG8_SB(0, 1), b2 + hstep, voffB); PG8_STAGE(PG8_SA(0, 0), a2, voffA);
.LBB0_869:
	ds_read_b128 v[154:157], v151
	ds_read_b128 v[158:161], v151 offset:1024
	ds_read_b128 v[162:165], v151 offset:2048
	ds_read_b128 v[166:169], v151 offset:3072
	ds_read_b128 v[170:173], v152
	ds_read_b128 v[174:177], v152 offset:1024
	ds_read_b128 v[178:181], v152 offset:2048
	ds_read_b128 v[182:185], v152 offset:3072
	s_add_u32 s42, s40, 0xfff80080
	s_addc_u32 s43, s41, -1
	s_cmp_eq_u32 s64, 28
	s_cselect_b32 s45, s31, s43
	s_cselect_b32 s44, s60, s42
	s_cselect_b32 s43, s29, s63
	s_cselect_b32 s42, s61, s62
	v_lshl_add_u64 v[146:147], s[40:41], 0, v[138:139]
	s_add_i32 m0, s39, 0xc000
	ds_read_b128 v[186:189], v153
	ds_read_b128 v[190:193], v153 offset:1024
	ds_read_b128 v[194:197], v153 offset:2048
	ds_read_b128 v[198:201], v153 offset:3072
	ds_read_b128 v[202:205], v153 offset:4096
	ds_read_b128 v[206:209], v153 offset:5120
	ds_read_b128 v[210:213], v153 offset:6144
	ds_read_b128 v[214:217], v153 offset:7168
	global_load_lds_dwordx4 v[146:147], off
	v_lshl_add_u64 v[146:147], s[40:41], 0, v[140:141]
	s_add_i32 m0, s39, 0xe000
	s_nop 0
	global_load_lds_dwordx4 v[146:147], off
	s_waitcnt vmcnt(8)
	s_waitcnt lgkmcnt(0)
	s_barrier
	s_waitcnt lgkmcnt(0)
	v_mfma_f32_16x16x32_bf16 v[126:129], v[154:157], v[186:189], v[126:129]
	v_mfma_f32_16x16x32_bf16 v[122:125], v[162:165], v[186:189], v[122:125]
	v_mfma_f32_16x16x32_bf16 v[110:113], v[154:157], v[194:197], v[110:113]
	v_mfma_f32_16x16x32_bf16 v[106:109], v[162:165], v[194:197], v[106:109]
	v_mfma_f32_16x16x32_bf16 v[94:97], v[154:157], v[202:205], v[94:97]
	v_mfma_f32_16x16x32_bf16 v[90:93], v[162:165], v[202:205], v[90:93]
	v_mfma_f32_16x16x32_bf16 v[78:81], v[154:157], v[210:213], v[78:81]
	v_mfma_f32_16x16x32_bf16 v[74:77], v[162:165], v[210:213], v[74:77]
	v_mfma_f32_16x16x32_bf16 v[126:129], v[158:161], v[190:193], v[126:129]
	v_mfma_f32_16x16x32_bf16 v[122:125], v[166:169], v[190:193], v[122:125]
	v_mfma_f32_16x16x32_bf16 v[110:113], v[158:161], v[198:201], v[110:113]
	v_mfma_f32_16x16x32_bf16 v[106:109], v[166:169], v[198:201], v[106:109]
	v_mfma_f32_16x16x32_bf16 v[94:97], v[158:161], v[206:209], v[94:97]
	v_mfma_f32_16x16x32_bf16 v[90:93], v[166:169], v[206:209], v[90:93]
	v_mfma_f32_16x16x32_bf16 v[78:81], v[158:161], v[214:217], v[78:81]
	v_mfma_f32_16x16x32_bf16 v[74:77], v[166:169], v[214:217], v[74:77]
	v_mfma_f32_16x16x32_bf16 v[118:121], v[170:173], v[186:189], v[118:121]
	v_mfma_f32_16x16x32_bf16 v[114:117], v[178:181], v[186:189], v[114:117]
	v_mfma_f32_16x16x32_bf16 v[102:105], v[170:173], v[194:197], v[102:105]
	v_mfma_f32_16x16x32_bf16 v[98:101], v[178:181], v[194:197], v[98:101]
	v_mfma_f32_16x16x32_bf16 v[86:89], v[170:173], v[202:205], v[86:89]
	v_mfma_f32_16x16x32_bf16 v[82:85], v[178:181], v[202:205], v[82:85]
	v_mfma_f32_16x16x32_bf16 v[70:73], v[170:173], v[210:213], v[70:73]
	v_mfma_f32_16x16x32_bf16 v[66:69], v[178:181], v[210:213], v[66:69]
	v_mfma_f32_16x16x32_bf16 v[118:121], v[174:177], v[190:193], v[118:121]
	v_mfma_f32_16x16x32_bf16 v[114:117], v[182:185], v[190:193], v[114:117]
	v_mfma_f32_16x16x32_bf16 v[102:105], v[174:177], v[198:201], v[102:105]
	v_mfma_f32_16x16x32_bf16 v[98:101], v[182:185], v[198:201], v[98:101]
	v_mfma_f32_16x16x32_bf16 v[86:89], v[174:177], v[206:209], v[86:89]
	v_mfma_f32_16x16x32_bf16 v[82:85], v[182:185], v[206:209], v[82:85]
	v_mfma_f32_16x16x32_bf16 v[70:73], v[174:177], v[214:217], v[70:73]
	v_mfma_f32_16x16x32_bf16 v[66:69], v[182:185], v[214:217], v[66:69]
	s_barrier
	s_add_i32 s65, s53, s33
	v_lshl_add_u64 v[146:147], s[42:43], 0, v[132:133]
	s_mov_b32 m0, s65
	ds_read_b128 v[186:189], v153 offset:16384
	ds_read_b128 v[190:193], v153 offset:17408
	ds_read_b128 v[194:197], v153 offset:18432
	ds_read_b128 v[198:201], v153 offset:19456
	ds_read_b128 v[202:205], v153 offset:20480
	ds_read_b128 v[206:209], v153 offset:21504
	ds_read_b128 v[210:213], v153 offset:22528
	ds_read_b128 v[214:217], v153 offset:23552
	global_load_lds_dwordx4 v[146:147], off
	s_add_i32 m0, s65, 0x2000
	s_add_u32 s66, s42, 0x80000
	v_lshl_add_u64 v[218:219], s[42:43], 0, v[136:137]
	s_addc_u32 s67, s43, 0
	s_add_i32 s65, s54, s33
	global_load_lds_dwordx4 v[218:219], off
	v_lshl_add_u64 v[220:221], s[66:67], 0, v[132:133]
	s_mov_b32 m0, s65
	v_lshl_add_u64 v[222:223], s[44:45], 0, v[134:135]
	global_load_lds_dwordx4 v[220:221], off
	v_lshl_add_u64 v[220:221], s[66:67], 0, v[136:137]
	s_add_i32 m0, s65, 0x2000
	s_nop 0
	global_load_lds_dwordx4 v[220:221], off
	v_lshl_add_u64 v[220:221], s[44:45], 0, v[130:131]
	s_mov_b32 m0, s39
	s_nop 0
	global_load_lds_dwordx4 v[220:221], off
	s_mov_b32 m0, s46
	s_nop 0
	global_load_lds_dwordx4 v[222:223], off
	s_waitcnt vmcnt(8)
	s_waitcnt lgkmcnt(0)
	s_barrier
; #define PG8_STAGE(bufoff, gbase, voff) do { _Pragma("unroll") for (int _i = 0; _i < 2; ++_i) \
;         __builtin_amdgcn_global_load_lds((const unsigned*)((const char*)(gbase) + (voff)[_i]), (LAS unsigned*)(lds + (bufoff) + ldsw + _i * 8192), 16, 0, 0); } while (0)
; #define PG8_LDA(dst, b, h) do { _Pragma("unroll") for (int m = 0; m < 4; ++m) _Pragma("unroll") for (int k = 0; k < 2; ++k) dst[m][k] = *(const LAS half8*)(lds + PG8_SA(b, h) + aoff + m * 2048 + k * 1024); } while (0)
; #define PG8_LDB(dst, b, h) do { _Pragma("unroll") for (int n = 0; n < 2; ++n) _Pragma("unroll") for (int k = 0; k < 2; ++k) dst[n][k] = *(const LAS half8*)(lds + PG8_SB(b, h) + boff + n * 2048 + k * 1024); } while (0)
; #define PG8_WAIT_V(n) asm volatile("s_waitcnt vmcnt(" #n ")" ::: "memory")
; #define PG8_WAIT_L(n) asm volatile("s_waitcnt lgkmcnt(" #n ")" ::: "memory")
; #define PG8_BAR __builtin_amdgcn_s_barrier()
; #define PG8_SCHED __builtin_amdgcn_sched_barrier(0)
; template <bool BF16, class Epi, class Sched, bool ALIGN_EPI = true, bool SP2 = true>
; __device__ __forceinline__ void gemm_phase(LAS unsigned char* lds, const Gemm g, const Sched& S, const Epi& E) {
;     ...
;             PG8_WAIT_V(8); PG8_WAIT_L(0); PG8_BAR; PG8_MMA(1, 0, At, B0); PG8_MMA(1, 1, At, B1); PG8_BAR; PG8_SCHED;
;             PG8_LDB(B0, 1, 0); PG8_LDB(B1, 1, 1); PG8_SCHED; PG8_LDA(At, 1, 0); PG8_STAGE(PG8_SA(0, 1), a2 + hstep, voffA);
;             PG8_WAIT_V(8); PG8_WAIT_L(0); PG8_BAR; PG8_MMA(0, 0, At, B0); PG8_MMA(0, 1, At, B1); PG8_BAR; PG8_SCHED;
	s_waitcnt lgkmcnt(0)
	v_mfma_f32_16x16x32_bf16 v[62:65], v[154:157], v[186:189], v[62:65]
	v_mfma_f32_16x16x32_bf16 v[58:61], v[162:165], v[186:189], v[58:61]
	v_mfma_f32_16x16x32_bf16 v[46:49], v[154:157], v[194:197], v[46:49]
	v_mfma_f32_16x16x32_bf16 v[42:45], v[162:165], v[194:197], v[42:45]
	v_mfma_f32_16x16x32_bf16 v[30:33], v[154:157], v[202:205], v[30:33]
	v_mfma_f32_16x16x32_bf16 v[26:29], v[162:165], v[202:205], v[26:29]
	v_mfma_f32_16x16x32_bf16 v[14:17], v[154:157], v[210:213], v[14:17]
	v_mfma_f32_16x16x32_bf16 v[10:13], v[162:165], v[210:213], v[10:13]
	v_mfma_f32_16x16x32_bf16 v[62:65], v[158:161], v[190:193], v[62:65]
	v_mfma_f32_16x16x32_bf16 v[58:61], v[166:169], v[190:193], v[58:61]
	v_mfma_f32_16x16x32_bf16 v[46:49], v[158:161], v[198:201], v[46:49]
	v_mfma_f32_16x16x32_bf16 v[42:45], v[166:169], v[198:201], v[42:45]
	v_mfma_f32_16x16x32_bf16 v[30:33], v[158:161], v[206:209], v[30:33]
	v_mfma_f32_16x16x32_bf16 v[26:29], v[166:169], v[206:209], v[26:29]
	v_mfma_f32_16x16x32_bf16 v[14:17], v[158:161], v[214:217], v[14:17]
	v_mfma_f32_16x16x32_bf16 v[10:13], v[166:169], v[214:217], v[10:13]
	v_mfma_f32_16x16x32_bf16 v[54:57], v[170:173], v[186:189], v[54:57]
	v_mfma_f32_16x16x32_bf16 v[50:53], v[178:181], v[186:189], v[50:53]
	v_mfma_f32_16x16x32_bf16 v[38:41], v[170:173], v[194:197], v[38:41]
	v_mfma_f32_16x16x32_bf16 v[34:37], v[178:181], v[194:197], v[34:37]
	v_mfma_f32_16x16x32_bf16 v[22:25], v[170:173], v[202:205], v[22:25]
	v_mfma_f32_16x16x32_bf16 v[18:21], v[178:181], v[202:205], v[18:21]
	v_mfma_f32_16x16x32_bf16 v[6:9], v[170:173], v[210:213], v[6:9]
	v_mfma_f32_16x16x32_bf16 v[2:5], v[178:181], v[210:213], v[2:5]
	v_mfma_f32_16x16x32_bf16 v[54:57], v[174:177], v[190:193], v[54:57]
	v_mfma_f32_16x16x32_bf16 v[50:53], v[182:185], v[190:193], v[50:53]
	v_mfma_f32_16x16x32_bf16 v[38:41], v[174:177], v[198:201], v[38:41]
	v_mfma_f32_16x16x32_bf16 v[34:37], v[182:185], v[198:201], v[34:37]
	v_mfma_f32_16x16x32_bf16 v[22:25], v[174:177], v[206:209], v[22:25]
	v_mfma_f32_16x16x32_bf16 v[18:21], v[182:185], v[206:209], v[18:21]
	v_mfma_f32_16x16x32_bf16 v[6:9], v[174:177], v[214:217], v[6:9]
	v_mfma_f32_16x16x32_bf16 v[2:5], v[182:185], v[214:217], v[2:5]
	s_barrier
	s_add_i32 s65, 0, 0x18000
	s_add_i32 s66, 0, 0x1c000
	v_add_u32_e32 v166, s65, v149
	v_add_u32_e32 v182, s66, v149
	ds_read_b128 v[154:157], v166
	ds_read_b128 v[158:161], v166 offset:1024
	ds_read_b128 v[162:165], v166 offset:2048
	ds_read_b128 v[166:169], v166 offset:3072
	ds_read_b128 v[170:173], v182
	ds_read_b128 v[174:177], v182 offset:1024
	ds_read_b128 v[178:181], v182 offset:2048
	ds_read_b128 v[182:185], v182 offset:3072
	s_add_u32 s44, s44, 0x80000
	s_addc_u32 s45, s45, 0
	s_mov_b32 m0, s47
	v_lshl_add_u64 v[224:225], s[44:45], 0, v[130:131]
	ds_read_b128 v[186:189], v153 offset:32768
	ds_read_b128 v[190:193], v153 offset:33792
	ds_read_b128 v[194:197], v153 offset:34816
	ds_read_b128 v[198:201], v153 offset:35840
	ds_read_b128 v[202:205], v153 offset:36864
	ds_read_b128 v[206:209], v153 offset:37888
	ds_read_b128 v[210:213], v153 offset:38912
	ds_read_b128 v[214:217], v153 offset:39936
	global_load_lds_dwordx4 v[224:225], off
	v_lshl_add_u64 v[224:225], s[44:45], 0, v[134:135]
	s_mov_b32 m0, s48
	s_nop 0
	global_load_lds_dwordx4 v[224:225], off
	s_waitcnt vmcnt(8)
	s_waitcnt lgkmcnt(0)
	s_barrier
	s_waitcnt lgkmcnt(0)
	v_mfma_f32_16x16x32_bf16 v[126:129], v[154:157], v[186:189], v[126:129]
	v_mfma_f32_16x16x32_bf16 v[122:125], v[162:165], v[186:189], v[122:125]
	v_mfma_f32_16x16x32_bf16 v[110:113], v[154:157], v[194:197], v[110:113]
	v_mfma_f32_16x16x32_bf16 v[106:109], v[162:165], v[194:197], v[106:109]
	v_mfma_f32_16x16x32_bf16 v[94:97], v[154:157], v[202:205], v[94:97]
	v_mfma_f32_16x16x32_bf16 v[90:93], v[162:165], v[202:205], v[90:93]
	v_mfma_f32_16x16x32_bf16 v[78:81], v[154:157], v[210:213], v[78:81]
	v_mfma_f32_16x16x32_bf16 v[74:77], v[162:165], v[210:213], v[74:77]
	v_mfma_f32_16x16x32_bf16 v[126:129], v[158:161], v[190:193], v[126:129]
	v_mfma_f32_16x16x32_bf16 v[122:125], v[166:169], v[190:193], v[122:125]
	v_mfma_f32_16x16x32_bf16 v[110:113], v[158:161], v[198:201], v[110:113]
	v_mfma_f32_16x16x32_bf16 v[106:109], v[166:169], v[198:201], v[106:109]
	v_mfma_f32_16x16x32_bf16 v[94:97], v[158:161], v[206:209], v[94:97]
	v_mfma_f32_16x16x32_bf16 v[90:93], v[166:169], v[206:209], v[90:93]
	v_mfma_f32_16x16x32_bf16 v[78:81], v[158:161], v[214:217], v[78:81]
	v_mfma_f32_16x16x32_bf16 v[74:77], v[166:169], v[214:217], v[74:77]
	v_mfma_f32_16x16x32_bf16 v[118:121], v[170:173], v[186:189], v[118:121]
	v_mfma_f32_16x16x32_bf16 v[114:117], v[178:181], v[186:189], v[114:117]
	v_mfma_f32_16x16x32_bf16 v[102:105], v[170:173], v[194:197], v[102:105]
	v_mfma_f32_16x16x32_bf16 v[98:101], v[178:181], v[194:197], v[98:101]
	v_mfma_f32_16x16x32_bf16 v[86:89], v[170:173], v[202:205], v[86:89]
	v_mfma_f32_16x16x32_bf16 v[82:85], v[178:181], v[202:205], v[82:85]
	v_mfma_f32_16x16x32_bf16 v[70:73], v[170:173], v[210:213], v[70:73]
	v_mfma_f32_16x16x32_bf16 v[66:69], v[178:181], v[210:213], v[66:69]
	v_mfma_f32_16x16x32_bf16 v[118:121], v[174:177], v[190:193], v[118:121]
	v_mfma_f32_16x16x32_bf16 v[114:117], v[182:185], v[190:193], v[114:117]
	v_mfma_f32_16x16x32_bf16 v[102:105], v[174:177], v[198:201], v[102:105]
	v_mfma_f32_16x16x32_bf16 v[98:101], v[182:185], v[198:201], v[98:101]
	v_mfma_f32_16x16x32_bf16 v[86:89], v[174:177], v[206:209], v[86:89]
	v_mfma_f32_16x16x32_bf16 v[82:85], v[182:185], v[206:209], v[82:85]
	v_mfma_f32_16x16x32_bf16 v[70:73], v[174:177], v[214:217], v[70:73]
	v_mfma_f32_16x16x32_bf16 v[66:69], v[182:185], v[214:217], v[66:69]
	s_barrier
; #define PG8_STAGE(bufoff, gbase, voff) do { _Pragma("unroll") for (int _i = 0; _i < 2; ++_i) \
;         __builtin_amdgcn_global_load_lds((const unsigned*)((const char*)(gbase) + (voff)[_i]), (LAS unsigned*)(lds + (bufoff) + ldsw + _i * 8192), 16, 0, 0); } while (0)
; #define PG8_LDA(dst, b, h) do { _Pragma("unroll") for (int m = 0; m < 4; ++m) _Pragma("unroll") for (int k = 0; k < 2; ++k) dst[m][k] = *(const LAS half8*)(lds + PG8_SA(b, h) + aoff + m * 2048 + k * 1024); } while (0)
; #define PG8_WAIT_V(n) asm volatile("s_waitcnt vmcnt(" #n ")" ::: "memory")
; template <bool BF16, class Epi, class Sched, bool ALIGN_EPI = true, bool SP2 = true>
; __device__ __forceinline__ void gemm_phase(LAS unsigned char* lds, const Gemm g, const Sched& S, const Epi& E) {
;     ...
;             PG8_LDA(At, 1, 1); PG8_STAGE(PG8_SB(1, 0), b3, voffB); PG8_STAGE(PG8_SB(1, 1), b3 + hstep, voffB); PG8_STAGE(PG8_SA(1, 0), a3, voffA);
;             PG8_WAIT_V(8); PG8_WAIT_L(0); PG8_BAR; PG8_MMA(1, 0, At, B0); PG8_MMA(1, 1, At, B1); PG8_BAR; PG8_SCHED;
;             } else {
;             PG8_LDB(B0, 0, 0); PG8_SCHED; PG8_LDA(At, 0, 0); PG8_STAGE(PG8_SA(1, 1), a1 + hstep, voffA);
;             PG8_WAIT_L(8); PG8_BAR; PG8_WAIT_L(0); PG8_MMA(0, 0, At, B0); PG8_BAR; PG8_SCHED;
;             PG8_LDB(B1, 0, 1); PG8_STAGE(PG8_SB(0, 0), b2, voffB);
;             PG8_BAR; PG8_WAIT_L(0); PG8_MMA(0, 1, At, B1); PG8_BAR;
;             PG8_LDA(At, 0, 1); PG8_STAGE(PG8_SA(0, 0), a2, voffA);
;             PG8_BAR; PG8_WAIT_L(0); PG8_MMA(1, 0, At, B0); PG8_BAR; PG8_SCHED;
;             PG8_STAGE(PG8_SB(0, 1), b2 + hstep, voffB);
;             PG8_WAIT_V(6); PG8_BAR; PG8_MMA(1, 1, At, B1); PG8_BAR;
;             PG8_LDB(B0, 1, 0); PG8_SCHED; PG8_LDA(At, 1, 0); PG8_STAGE(PG8_SA(0, 1), a2 + hstep, voffA);
;             PG8_WAIT_L(8); PG8_BAR; PG8_WAIT_L(0); PG8_MMA(0, 0, At, B0); PG8_BAR; PG8_SCHED;
;             PG8_LDB(B1, 1, 1); PG8_STAGE(PG8_SB(1, 0), b3, voffB);
;             PG8_BAR; PG8_WAIT_L(0); PG8_MMA(0, 1, At, B1); PG8_BAR;
;             PG8_LDA(At, 1, 1); PG8_STAGE(PG8_SA(1, 0), a3, voffA);
;             PG8_BAR; PG8_WAIT_L(0); PG8_MMA(1, 0, At, B0); PG8_BAR; PG8_SCHED;
;             PG8_STAGE(PG8_SB(1, 1), b3 + hstep, voffB);
;             PG8_WAIT_V(6); PG8_BAR; PG8_MMA(1, 1, At, B1); PG8_BAR;
;             }
;         }
;         if constexpr (ALIGN_EPI) { if (wr == 0) PG8_BAR; }
	s_add_i32 s44, s65, s33
	v_lshl_add_u64 v[146:147], v[146:147], 0, s[10:11]
	s_mov_b32 m0, s44
	ds_read_b128 v[186:189], v153 offset:49152
	ds_read_b128 v[190:193], v153 offset:50176
	ds_read_b128 v[194:197], v153 offset:51200
	ds_read_b128 v[198:201], v153 offset:52224
	ds_read_b128 v[202:205], v153 offset:53248
	ds_read_b128 v[206:209], v153 offset:54272
	ds_read_b128 v[210:213], v153 offset:55296
	ds_read_b128 v[214:217], v153 offset:56320
	global_load_lds_dwordx4 v[146:147], off
	s_add_i32 m0, s44, 0x2000
	s_add_u32 s42, s42, 0x80080
	v_lshl_add_u64 v[146:147], v[218:219], 0, s[10:11]
	s_addc_u32 s43, s43, 0
	s_add_i32 s44, s66, s33
	global_load_lds_dwordx4 v[146:147], off
	v_lshl_add_u64 v[146:147], s[42:43], 0, v[132:133]
	s_mov_b32 m0, s44
	s_nop 0
	global_load_lds_dwordx4 v[146:147], off
	v_lshl_add_u64 v[146:147], s[42:43], 0, v[136:137]
	s_add_i32 m0, s44, 0x2000
	s_nop 0
	global_load_lds_dwordx4 v[146:147], off
	v_lshl_add_u64 v[146:147], v[220:221], 0, s[10:11]
	s_mov_b32 m0, s50
	s_nop 0
	global_load_lds_dwordx4 v[146:147], off
	v_lshl_add_u64 v[146:147], v[222:223], 0, s[10:11]
	s_mov_b32 m0, s51
	s_nop 0
	global_load_lds_dwordx4 v[146:147], off
	s_waitcnt vmcnt(8)
	s_waitcnt lgkmcnt(0)
	s_barrier
	s_waitcnt lgkmcnt(0)
	v_mfma_f32_16x16x32_bf16 v[62:65], v[154:157], v[186:189], v[62:65]
	v_mfma_f32_16x16x32_bf16 v[58:61], v[162:165], v[186:189], v[58:61]
	v_mfma_f32_16x16x32_bf16 v[46:49], v[154:157], v[194:197], v[46:49]
	v_mfma_f32_16x16x32_bf16 v[42:45], v[162:165], v[194:197], v[42:45]
	v_mfma_f32_16x16x32_bf16 v[30:33], v[154:157], v[202:205], v[30:33]
	v_mfma_f32_16x16x32_bf16 v[26:29], v[162:165], v[202:205], v[26:29]
	v_mfma_f32_16x16x32_bf16 v[14:17], v[154:157], v[210:213], v[14:17]
	v_mfma_f32_16x16x32_bf16 v[10:13], v[162:165], v[210:213], v[10:13]
	v_mfma_f32_16x16x32_bf16 v[62:65], v[158:161], v[190:193], v[62:65]
	v_mfma_f32_16x16x32_bf16 v[58:61], v[166:169], v[190:193], v[58:61]
	v_mfma_f32_16x16x32_bf16 v[46:49], v[158:161], v[198:201], v[46:49]
	v_mfma_f32_16x16x32_bf16 v[42:45], v[166:169], v[198:201], v[42:45]
	v_mfma_f32_16x16x32_bf16 v[30:33], v[158:161], v[206:209], v[30:33]
	v_mfma_f32_16x16x32_bf16 v[26:29], v[166:169], v[206:209], v[26:29]
	v_mfma_f32_16x16x32_bf16 v[14:17], v[158:161], v[214:217], v[14:17]
	v_mfma_f32_16x16x32_bf16 v[10:13], v[166:169], v[214:217], v[10:13]
	v_mfma_f32_16x16x32_bf16 v[54:57], v[170:173], v[186:189], v[54:57]
	v_mfma_f32_16x16x32_bf16 v[50:53], v[178:181], v[186:189], v[50:53]
	v_mfma_f32_16x16x32_bf16 v[38:41], v[170:173], v[194:197], v[38:41]
	v_mfma_f32_16x16x32_bf16 v[34:37], v[178:181], v[194:197], v[34:37]
	v_mfma_f32_16x16x32_bf16 v[22:25], v[170:173], v[202:205], v[22:25]
	v_mfma_f32_16x16x32_bf16 v[18:21], v[178:181], v[202:205], v[18:21]
	v_mfma_f32_16x16x32_bf16 v[6:9], v[170:173], v[210:213], v[6:9]
	v_mfma_f32_16x16x32_bf16 v[2:5], v[178:181], v[210:213], v[2:5]
	v_mfma_f32_16x16x32_bf16 v[54:57], v[174:177], v[190:193], v[54:57]
	v_mfma_f32_16x16x32_bf16 v[50:53], v[182:185], v[190:193], v[50:53]
	v_mfma_f32_16x16x32_bf16 v[38:41], v[174:177], v[198:201], v[38:41]
	v_mfma_f32_16x16x32_bf16 v[34:37], v[182:185], v[198:201], v[34:37]
	v_mfma_f32_16x16x32_bf16 v[22:25], v[174:177], v[206:209], v[22:25]
	v_mfma_f32_16x16x32_bf16 v[18:21], v[182:185], v[206:209], v[18:21]
	v_mfma_f32_16x16x32_bf16 v[6:9], v[174:177], v[214:217], v[6:9]
	v_mfma_f32_16x16x32_bf16 v[2:5], v[182:185], v[214:217], v[2:5]
	s_barrier
	s_add_i32 s64, s64, 2
	s_add_u32 s40, s40, 0x100
	s_addc_u32 s41, s41, 0
	s_add_u32 s62, s62, 0x100
	s_addc_u32 s63, s63, 0
	s_cmp_gt_u32 s64, 29
	s_cbranch_scc0 .LBB0_869
	s_and_b64 vcc, exec, s[12:13]
	s_cbranch_vccz .LBB0_872
	s_barrier

; #define PHASE_BEGIN(n) if (lo <= (n) && (n) < hi) {
; #define PHASE_END(n) if ((n) + 1 < hi) { if (G != 256) cg::this_grid().sync(); else xcd_barrier(xbar); } }
;     __host__ __device__ bool next(int i, Unit& u) const {
;         const long L = (long)i * G + c; if (L >= nwg) return false;
;         int wgid = (int)L; { const int q = nwg / NXCD, r = nwg % NXCD, xcd = wgid % NXCD, off = wgid / NXCD; wgid = (xcd < r ? xcd * (q + 1) : r * (q + 1) + (xcd - r) * q) + off; }
;         const int nig = WGM * nN, gid = wgid / nig, fm = gid * WGM, gsz = (nM - fm) < WGM ? (nM - fm) : WGM;
;         u.pm = fm + ((wgid % nig) % gsz); u.pn = (wgid % nig) / gsz; return true;
; __global__ void __launch_bounds__(NTHR, 2) mega(Args args) {
;     ...
;     PHASE_BEGIN(10) { pg8::Gemm g{(const h16*)(ws + WS_HID), (const h16*)(ws + WS_W2), NT, DM, DFF}; pg8::StaticOrder S; S.init(NT, DM, G, bid);
;                    pg8::EpiRes<false> E{ws + WS_X1H, (h16*)(ws + WS_X1H), mod + 5 * 2048, 12288}; pg8::gemm_phase<true>(lds, g, S, E); } PHASE_END(10)
.LBB0_940:
	s_cmp_lt_i32 s26, 11
	s_cselect_b64 s[0:1], -1, 0
	s_cmp_gt_i32 s27, 10
	s_cselect_b64 s[4:5], -1, 0
	s_and_b64 s[0:1], s[0:1], s[4:5]
	s_andn2_b64 vcc, exec, s[0:1]
	s_cbranch_vccnz .LBB0_1029
	s_cmpk_gt_i32 s2, 0x3ff
	v_readfirstlane_b32 s12, v1
	s_cbranch_scc1 .LBB0_965
	s_bitcmp1_b32 s12, 8
	s_cbranch_scc0 .Lprio_g19861
	s_setprio 1
.Lprio_g19861:
	s_ashr_i32 s0, s2, 31
	s_lshr_b32 s1, s0, 29
	s_add_i32 s3, s2, s1
	s_and_b32 s1, s3, -8
	s_sub_i32 s1, s2, s1
	s_cmp_gt_i32 s1, -1
	s_cbranch_scc0 .LBB0_944
	s_lshl_b32 s6, s1, 7
	s_ashr_i32 s4, s3, 3
	s_cbranch_execz .LBB0_945
	s_branch .LBB0_946

; #define PG8_STAGE(bufoff, gbase, voff) do { _Pragma("unroll") for (int _i = 0; _i < 2; ++_i) \
;         __builtin_amdgcn_global_load_lds((const unsigned*)((const char*)(gbase) + (voff)[_i]), (LAS unsigned*)(lds + (bufoff) + ldsw + _i * 8192), 16, 0, 0); } while (0)
; #define PG8_LDA(dst, b, h) do { _Pragma("unroll") for (int m = 0; m < 4; ++m) _Pragma("unroll") for (int k = 0; k < 2; ++k) dst[m][k] = *(const LAS half8*)(lds + PG8_SA(b, h) + aoff + m * 2048 + k * 1024); } while (0)
; #define PG8_LDB(dst, b, h) do { _Pragma("unroll") for (int n = 0; n < 2; ++n) _Pragma("unroll") for (int k = 0; k < 2; ++k) dst[n][k] = *(const LAS half8*)(lds + PG8_SB(b, h) + boff + n * 2048 + k * 1024); } while (0)
; #define PG8_WAIT_V(n) asm volatile("s_waitcnt vmcnt(" #n ")" ::: "memory")
; #define PG8_WAIT_L(n) asm volatile("s_waitcnt lgkmcnt(" #n ")" ::: "memory")
; #define PG8_BAR __builtin_amdgcn_s_barrier()
; #define PG8_SCHED __builtin_amdgcn_sched_barrier(0)
; template <bool BF16, class Epi, class Sched, bool ALIGN_EPI = true, bool SP2 = true>
; __device__ __forceinline__ void gemm_phase(LAS unsigned char* lds, const Gemm g, const Sched& S, const Epi& E) {
;     ...
;             PG8_LDB(B0, 0, 0); PG8_LDB(B1, 0, 1); PG8_SCHED; PG8_LDA(At, 0, 0); PG8_STAGE(PG8_SA(1, 1), a1 + hstep, voffA);
;             PG8_WAIT_V(8); PG8_WAIT_L(0); PG8_BAR; PG8_MMA(0, 0, At, B0); PG8_MMA(0, 1, At, B1); PG8_BAR; PG8_SCHED;
;             PG8_LDA(At, 0, 1); PG8_STAGE(PG8_SB(0, 0), b2, voffB); PG8_STAGE(PG8_SB(0, 1), b2 + hstep, voffB); PG8_STAGE(PG8_SA(0, 0), a2, voffA);
.LBB0_958:
	ds_read_b128 v[130:133], v181
	ds_read_b128 v[134:137], v181 offset:1024
	ds_read_b128 v[138:141], v181 offset:2048
	ds_read_b128 v[142:145], v181 offset:3072
	ds_read_b128 v[146:149], v182
	ds_read_b128 v[150:153], v182 offset:1024
	ds_read_b128 v[170:173], v182 offset:2048
	ds_read_b128 v[174:177], v182 offset:3072
	s_add_u32 s42, s40, 0xffe00080
	s_addc_u32 s43, s41, -1
	s_cmpk_eq_i32 s66, 0x7c
	s_cselect_b32 s45, s31, s43
	s_cselect_b32 s44, s62, s42
	s_cselect_b32 s43, s29, s65
	s_cselect_b32 s42, s63, s64
	v_lshl_add_u64 v[216:217], s[40:41], 0, v[162:163]
	s_add_i32 m0, s39, 0xc000
	ds_read_b128 v[184:187], v183
	ds_read_b128 v[188:191], v183 offset:1024
	ds_read_b128 v[192:195], v183 offset:2048
	ds_read_b128 v[196:199], v183 offset:3072
	ds_read_b128 v[200:203], v183 offset:4096
	ds_read_b128 v[204:207], v183 offset:5120
	ds_read_b128 v[208:211], v183 offset:6144
	ds_read_b128 v[212:215], v183 offset:7168
	global_load_lds_dwordx4 v[216:217], off
	v_lshl_add_u64 v[216:217], s[40:41], 0, v[164:165]
	s_add_i32 m0, s39, 0xe000
	s_nop 0
	global_load_lds_dwordx4 v[216:217], off
	s_waitcnt vmcnt(8)
	s_waitcnt lgkmcnt(0)
	s_barrier
	s_waitcnt lgkmcnt(0)
	v_mfma_f32_16x16x32_bf16 v[126:129], v[130:133], v[184:187], v[126:129]
	v_mfma_f32_16x16x32_bf16 v[122:125], v[138:141], v[184:187], v[122:125]
	v_mfma_f32_16x16x32_bf16 v[118:121], v[130:133], v[192:195], v[118:121]
	v_mfma_f32_16x16x32_bf16 v[114:117], v[138:141], v[192:195], v[114:117]
	v_mfma_f32_16x16x32_bf16 v[94:97], v[130:133], v[200:203], v[94:97]
	v_mfma_f32_16x16x32_bf16 v[90:93], v[138:141], v[200:203], v[90:93]
	v_mfma_f32_16x16x32_bf16 v[78:81], v[130:133], v[208:211], v[78:81]
	v_mfma_f32_16x16x32_bf16 v[74:77], v[138:141], v[208:211], v[74:77]
	v_mfma_f32_16x16x32_bf16 v[126:129], v[134:137], v[188:191], v[126:129]
	v_mfma_f32_16x16x32_bf16 v[122:125], v[142:145], v[188:191], v[122:125]
	v_mfma_f32_16x16x32_bf16 v[118:121], v[134:137], v[196:199], v[118:121]
	v_mfma_f32_16x16x32_bf16 v[114:117], v[142:145], v[196:199], v[114:117]
	v_mfma_f32_16x16x32_bf16 v[94:97], v[134:137], v[204:207], v[94:97]
	v_mfma_f32_16x16x32_bf16 v[90:93], v[142:145], v[204:207], v[90:93]
	v_mfma_f32_16x16x32_bf16 v[78:81], v[134:137], v[212:215], v[78:81]
	v_mfma_f32_16x16x32_bf16 v[74:77], v[142:145], v[212:215], v[74:77]
	v_mfma_f32_16x16x32_bf16 v[110:113], v[146:149], v[184:187], v[110:113]
	v_mfma_f32_16x16x32_bf16 v[106:109], v[170:173], v[184:187], v[106:109]
	v_mfma_f32_16x16x32_bf16 v[102:105], v[146:149], v[192:195], v[102:105]
	v_mfma_f32_16x16x32_bf16 v[98:101], v[170:173], v[192:195], v[98:101]
	v_mfma_f32_16x16x32_bf16 v[86:89], v[146:149], v[200:203], v[86:89]
	v_mfma_f32_16x16x32_bf16 v[82:85], v[170:173], v[200:203], v[82:85]
	v_mfma_f32_16x16x32_bf16 v[70:73], v[146:149], v[208:211], v[70:73]
	v_mfma_f32_16x16x32_bf16 v[66:69], v[170:173], v[208:211], v[66:69]
	v_mfma_f32_16x16x32_bf16 v[110:113], v[150:153], v[188:191], v[110:113]
	v_mfma_f32_16x16x32_bf16 v[106:109], v[174:177], v[188:191], v[106:109]
	v_mfma_f32_16x16x32_bf16 v[102:105], v[150:153], v[196:199], v[102:105]
	v_mfma_f32_16x16x32_bf16 v[98:101], v[174:177], v[196:199], v[98:101]
	v_mfma_f32_16x16x32_bf16 v[86:89], v[150:153], v[204:207], v[86:89]
	v_mfma_f32_16x16x32_bf16 v[82:85], v[174:177], v[204:207], v[82:85]
	v_mfma_f32_16x16x32_bf16 v[70:73], v[150:153], v[212:215], v[70:73]
	v_mfma_f32_16x16x32_bf16 v[66:69], v[174:177], v[212:215], v[66:69]
	s_barrier
	s_add_i32 s67, s55, s33
	v_lshl_add_u64 v[216:217], s[42:43], 0, v[156:157]
	s_mov_b32 m0, s67
	ds_read_b128 v[184:187], v183 offset:16384
	ds_read_b128 v[188:191], v183 offset:17408
	ds_read_b128 v[192:195], v183 offset:18432
	ds_read_b128 v[196:199], v183 offset:19456
	ds_read_b128 v[200:203], v183 offset:20480
	ds_read_b128 v[204:207], v183 offset:21504
	ds_read_b128 v[208:211], v183 offset:22528
	ds_read_b128 v[212:215], v183 offset:23552
	global_load_lds_dwordx4 v[216:217], off
	s_add_i32 m0, s67, 0x2000
	s_add_u32 s68, s42, 0x200000
	v_lshl_add_u64 v[218:219], s[42:43], 0, v[160:161]
	s_addc_u32 s69, s43, 0
	s_add_i32 s67, s56, s33
	global_load_lds_dwordx4 v[218:219], off
	v_lshl_add_u64 v[220:221], s[68:69], 0, v[156:157]
	s_mov_b32 m0, s67
	v_lshl_add_u64 v[222:223], s[44:45], 0, v[158:159]
	global_load_lds_dwordx4 v[220:221], off
	v_lshl_add_u64 v[220:221], s[68:69], 0, v[160:161]
	s_add_i32 m0, s67, 0x2000
	s_nop 0
	global_load_lds_dwordx4 v[220:221], off
	v_lshl_add_u64 v[220:221], s[44:45], 0, v[154:155]
	s_mov_b32 m0, s39
	s_nop 0
	global_load_lds_dwordx4 v[220:221], off
	s_mov_b32 m0, s46
	s_nop 0
	global_load_lds_dwordx4 v[222:223], off
	s_waitcnt vmcnt(8)
	s_waitcnt lgkmcnt(0)
	s_barrier
; #define PG8_STAGE(bufoff, gbase, voff) do { _Pragma("unroll") for (int _i = 0; _i < 2; ++_i) \
;         __builtin_amdgcn_global_load_lds((const unsigned*)((const char*)(gbase) + (voff)[_i]), (LAS unsigned*)(lds + (bufoff) + ldsw + _i * 8192), 16, 0, 0); } while (0)
; #define PG8_LDA(dst, b, h) do { _Pragma("unroll") for (int m = 0; m < 4; ++m) _Pragma("unroll") for (int k = 0; k < 2; ++k) dst[m][k] = *(const LAS half8*)(lds + PG8_SA(b, h) + aoff + m * 2048 + k * 1024); } while (0)
; #define PG8_LDB(dst, b, h) do { _Pragma("unroll") for (int n = 0; n < 2; ++n) _Pragma("unroll") for (int k = 0; k < 2; ++k) dst[n][k] = *(const LAS half8*)(lds + PG8_SB(b, h) + boff + n * 2048 + k * 1024); } while (0)
; #define PG8_WAIT_V(n) asm volatile("s_waitcnt vmcnt(" #n ")" ::: "memory")
; #define PG8_WAIT_L(n) asm volatile("s_waitcnt lgkmcnt(" #n ")" ::: "memory")
; #define PG8_BAR __builtin_amdgcn_s_barrier()
; #define PG8_SCHED __builtin_amdgcn_sched_barrier(0)
; template <bool BF16, class Epi, class Sched, bool ALIGN_EPI = true, bool SP2 = true>
; __device__ __forceinline__ void gemm_phase(LAS unsigned char* lds, const Gemm g, const Sched& S, const Epi& E) {
;     ...
;             PG8_WAIT_V(8); PG8_WAIT_L(0); PG8_BAR; PG8_MMA(1, 0, At, B0); PG8_MMA(1, 1, At, B1); PG8_BAR; PG8_SCHED;
;             PG8_LDB(B0, 1, 0); PG8_LDB(B1, 1, 1); PG8_SCHED; PG8_LDA(At, 1, 0); PG8_STAGE(PG8_SA(0, 1), a2 + hstep, voffA);
;             PG8_WAIT_V(8); PG8_WAIT_L(0); PG8_BAR; PG8_MMA(0, 0, At, B0); PG8_MMA(0, 1, At, B1); PG8_BAR; PG8_SCHED;
	s_waitcnt lgkmcnt(0)
	v_mfma_f32_16x16x32_bf16 v[62:65], v[130:133], v[184:187], v[62:65]
	v_mfma_f32_16x16x32_bf16 v[58:61], v[138:141], v[184:187], v[58:61]
	v_mfma_f32_16x16x32_bf16 v[46:49], v[130:133], v[192:195], v[46:49]
	v_mfma_f32_16x16x32_bf16 v[42:45], v[138:141], v[192:195], v[42:45]
	v_mfma_f32_16x16x32_bf16 v[38:41], v[130:133], v[200:203], v[38:41]
	v_mfma_f32_16x16x32_bf16 v[34:37], v[138:141], v[200:203], v[34:37]
	v_mfma_f32_16x16x32_bf16 v[22:25], v[130:133], v[208:211], v[22:25]
	v_mfma_f32_16x16x32_bf16 v[18:21], v[138:141], v[208:211], v[18:21]
	v_mfma_f32_16x16x32_bf16 v[62:65], v[134:137], v[188:191], v[62:65]
	v_mfma_f32_16x16x32_bf16 v[58:61], v[142:145], v[188:191], v[58:61]
	v_mfma_f32_16x16x32_bf16 v[46:49], v[134:137], v[196:199], v[46:49]
	v_mfma_f32_16x16x32_bf16 v[42:45], v[142:145], v[196:199], v[42:45]
	v_mfma_f32_16x16x32_bf16 v[38:41], v[134:137], v[204:207], v[38:41]
	v_mfma_f32_16x16x32_bf16 v[34:37], v[142:145], v[204:207], v[34:37]
	v_mfma_f32_16x16x32_bf16 v[22:25], v[134:137], v[212:215], v[22:25]
	v_mfma_f32_16x16x32_bf16 v[18:21], v[142:145], v[212:215], v[18:21]
	v_mfma_f32_16x16x32_bf16 v[54:57], v[146:149], v[184:187], v[54:57]
	v_mfma_f32_16x16x32_bf16 v[50:53], v[170:173], v[184:187], v[50:53]
	v_mfma_f32_16x16x32_bf16 v[30:33], v[146:149], v[192:195], v[30:33]
	v_mfma_f32_16x16x32_bf16 v[26:29], v[170:173], v[192:195], v[26:29]
	v_mfma_f32_16x16x32_bf16 v[14:17], v[146:149], v[200:203], v[14:17]
	v_mfma_f32_16x16x32_bf16 v[10:13], v[170:173], v[200:203], v[10:13]
	v_mfma_f32_16x16x32_bf16 v[6:9], v[146:149], v[208:211], v[6:9]
	v_mfma_f32_16x16x32_bf16 v[2:5], v[170:173], v[208:211], v[2:5]
	v_mfma_f32_16x16x32_bf16 v[54:57], v[150:153], v[188:191], v[54:57]
	v_mfma_f32_16x16x32_bf16 v[50:53], v[174:177], v[188:191], v[50:53]
	v_mfma_f32_16x16x32_bf16 v[30:33], v[150:153], v[196:199], v[30:33]
	v_mfma_f32_16x16x32_bf16 v[26:29], v[174:177], v[196:199], v[26:29]
	v_mfma_f32_16x16x32_bf16 v[14:17], v[150:153], v[204:207], v[14:17]
	v_mfma_f32_16x16x32_bf16 v[10:13], v[174:177], v[204:207], v[10:13]
	v_mfma_f32_16x16x32_bf16 v[6:9], v[150:153], v[212:215], v[6:9]
	v_mfma_f32_16x16x32_bf16 v[2:5], v[174:177], v[212:215], v[2:5]
	s_barrier
	s_add_i32 s67, 0, 0x18000
	s_add_i32 s68, 0, 0x1c000
	v_add_u32_e32 v142, s67, v179
	v_add_u32_e32 v174, s68, v179
	ds_read_b128 v[130:133], v142
	ds_read_b128 v[134:137], v142 offset:1024
	ds_read_b128 v[138:141], v142 offset:2048
	ds_read_b128 v[142:145], v142 offset:3072
	ds_read_b128 v[146:149], v174
	ds_read_b128 v[150:153], v174 offset:1024
	ds_read_b128 v[170:173], v174 offset:2048
	ds_read_b128 v[174:177], v174 offset:3072
	s_add_u32 s44, s44, 0x200000
	s_addc_u32 s45, s45, 0
	s_mov_b32 m0, s47
	v_lshl_add_u64 v[224:225], s[44:45], 0, v[154:155]
	ds_read_b128 v[184:187], v183 offset:32768
	ds_read_b128 v[188:191], v183 offset:33792
	ds_read_b128 v[192:195], v183 offset:34816
	ds_read_b128 v[196:199], v183 offset:35840
	ds_read_b128 v[200:203], v183 offset:36864
	ds_read_b128 v[204:207], v183 offset:37888
	ds_read_b128 v[208:211], v183 offset:38912
	ds_read_b128 v[212:215], v183 offset:39936
	global_load_lds_dwordx4 v[224:225], off
	v_lshl_add_u64 v[224:225], s[44:45], 0, v[158:159]
	s_mov_b32 m0, s48
	s_nop 0
	global_load_lds_dwordx4 v[224:225], off
	s_waitcnt vmcnt(8)
	s_waitcnt lgkmcnt(0)
	s_barrier
	s_waitcnt lgkmcnt(0)
	v_mfma_f32_16x16x32_bf16 v[126:129], v[130:133], v[184:187], v[126:129]
	v_mfma_f32_16x16x32_bf16 v[122:125], v[138:141], v[184:187], v[122:125]
	v_mfma_f32_16x16x32_bf16 v[118:121], v[130:133], v[192:195], v[118:121]
	v_mfma_f32_16x16x32_bf16 v[114:117], v[138:141], v[192:195], v[114:117]
	v_mfma_f32_16x16x32_bf16 v[94:97], v[130:133], v[200:203], v[94:97]
	v_mfma_f32_16x16x32_bf16 v[90:93], v[138:141], v[200:203], v[90:93]
	v_mfma_f32_16x16x32_bf16 v[78:81], v[130:133], v[208:211], v[78:81]
	v_mfma_f32_16x16x32_bf16 v[74:77], v[138:141], v[208:211], v[74:77]
	v_mfma_f32_16x16x32_bf16 v[126:129], v[134:137], v[188:191], v[126:129]
	v_mfma_f32_16x16x32_bf16 v[122:125], v[142:145], v[188:191], v[122:125]
	v_mfma_f32_16x16x32_bf16 v[118:121], v[134:137], v[196:199], v[118:121]
	v_mfma_f32_16x16x32_bf16 v[114:117], v[142:145], v[196:199], v[114:117]
	v_mfma_f32_16x16x32_bf16 v[94:97], v[134:137], v[204:207], v[94:97]
	v_mfma_f32_16x16x32_bf16 v[90:93], v[142:145], v[204:207], v[90:93]
	v_mfma_f32_16x16x32_bf16 v[78:81], v[134:137], v[212:215], v[78:81]
	v_mfma_f32_16x16x32_bf16 v[74:77], v[142:145], v[212:215], v[74:77]
	v_mfma_f32_16x16x32_bf16 v[110:113], v[146:149], v[184:187], v[110:113]
	v_mfma_f32_16x16x32_bf16 v[106:109], v[170:173], v[184:187], v[106:109]
	v_mfma_f32_16x16x32_bf16 v[102:105], v[146:149], v[192:195], v[102:105]
	v_mfma_f32_16x16x32_bf16 v[98:101], v[170:173], v[192:195], v[98:101]
	v_mfma_f32_16x16x32_bf16 v[86:89], v[146:149], v[200:203], v[86:89]
	v_mfma_f32_16x16x32_bf16 v[82:85], v[170:173], v[200:203], v[82:85]
	v_mfma_f32_16x16x32_bf16 v[70:73], v[146:149], v[208:211], v[70:73]
	v_mfma_f32_16x16x32_bf16 v[66:69], v[170:173], v[208:211], v[66:69]
	v_mfma_f32_16x16x32_bf16 v[110:113], v[150:153], v[188:191], v[110:113]
	v_mfma_f32_16x16x32_bf16 v[106:109], v[174:177], v[188:191], v[106:109]
	v_mfma_f32_16x16x32_bf16 v[102:105], v[150:153], v[196:199], v[102:105]
	v_mfma_f32_16x16x32_bf16 v[98:101], v[174:177], v[196:199], v[98:101]
	v_mfma_f32_16x16x32_bf16 v[86:89], v[150:153], v[204:207], v[86:89]
	v_mfma_f32_16x16x32_bf16 v[82:85], v[174:177], v[204:207], v[82:85]
	v_mfma_f32_16x16x32_bf16 v[70:73], v[150:153], v[212:215], v[70:73]
	v_mfma_f32_16x16x32_bf16 v[66:69], v[174:177], v[212:215], v[66:69]
	s_barrier
; #define PG8_STAGE(bufoff, gbase, voff) do { _Pragma("unroll") for (int _i = 0; _i < 2; ++_i) \
;         __builtin_amdgcn_global_load_lds((const unsigned*)((const char*)(gbase) + (voff)[_i]), (LAS unsigned*)(lds + (bufoff) + ldsw + _i * 8192), 16, 0, 0); } while (0)
; #define PG8_LDA(dst, b, h) do { _Pragma("unroll") for (int m = 0; m < 4; ++m) _Pragma("unroll") for (int k = 0; k < 2; ++k) dst[m][k] = *(const LAS half8*)(lds + PG8_SA(b, h) + aoff + m * 2048 + k * 1024); } while (0)
; #define PG8_WAIT_V(n) asm volatile("s_waitcnt vmcnt(" #n ")" ::: "memory")
; template <bool BF16, class Epi, class Sched, bool ALIGN_EPI = true, bool SP2 = true>
; __device__ __forceinline__ void gemm_phase(LAS unsigned char* lds, const Gemm g, const Sched& S, const Epi& E) {
;     ...
;             PG8_LDA(At, 1, 1); PG8_STAGE(PG8_SB(1, 0), b3, voffB); PG8_STAGE(PG8_SB(1, 1), b3 + hstep, voffB); PG8_STAGE(PG8_SA(1, 0), a3, voffA);
;             PG8_WAIT_V(8); PG8_WAIT_L(0); PG8_BAR; PG8_MMA(1, 0, At, B0); PG8_MMA(1, 1, At, B1); PG8_BAR; PG8_SCHED;
;             } else {
;             PG8_LDB(B0, 0, 0); PG8_SCHED; PG8_LDA(At, 0, 0); PG8_STAGE(PG8_SA(1, 1), a1 + hstep, voffA);
;             PG8_WAIT_L(8); PG8_BAR; PG8_WAIT_L(0); PG8_MMA(0, 0, At, B0); PG8_BAR; PG8_SCHED;
;             PG8_LDB(B1, 0, 1); PG8_STAGE(PG8_SB(0, 0), b2, voffB);
;             PG8_BAR; PG8_WAIT_L(0); PG8_MMA(0, 1, At, B1); PG8_BAR;
;             PG8_LDA(At, 0, 1); PG8_STAGE(PG8_SA(0, 0), a2, voffA);
;             PG8_BAR; PG8_WAIT_L(0); PG8_MMA(1, 0, At, B0); PG8_BAR; PG8_SCHED;
;             PG8_STAGE(PG8_SB(0, 1), b2 + hstep, voffB);
;             PG8_WAIT_V(6); PG8_BAR; PG8_MMA(1, 1, At, B1); PG8_BAR;
;             PG8_LDB(B0, 1, 0); PG8_SCHED; PG8_LDA(At, 1, 0); PG8_STAGE(PG8_SA(0, 1), a2 + hstep, voffA);
;             PG8_WAIT_L(8); PG8_BAR; PG8_WAIT_L(0); PG8_MMA(0, 0, At, B0); PG8_BAR; PG8_SCHED;
;             PG8_LDB(B1, 1, 1); PG8_STAGE(PG8_SB(1, 0), b3, voffB);
;             PG8_BAR; PG8_WAIT_L(0); PG8_MMA(0, 1, At, B1); PG8_BAR;
;             PG8_LDA(At, 1, 1); PG8_STAGE(PG8_SA(1, 0), a3, voffA);
;             PG8_BAR; PG8_WAIT_L(0); PG8_MMA(1, 0, At, B0); PG8_BAR; PG8_SCHED;
;             PG8_STAGE(PG8_SB(1, 1), b3 + hstep, voffB);
;             PG8_WAIT_V(6); PG8_BAR; PG8_MMA(1, 1, At, B1); PG8_BAR;
;             }
;         }
;         if constexpr (ALIGN_EPI) { if (wr == 0) PG8_BAR; }
	s_add_i32 s44, s67, s33
	v_lshl_add_u64 v[216:217], v[216:217], 0, s[10:11]
	s_mov_b32 m0, s44
	ds_read_b128 v[184:187], v183 offset:49152
	ds_read_b128 v[188:191], v183 offset:50176
	ds_read_b128 v[192:195], v183 offset:51200
	ds_read_b128 v[196:199], v183 offset:52224
	ds_read_b128 v[200:203], v183 offset:53248
	ds_read_b128 v[204:207], v183 offset:54272
	ds_read_b128 v[208:211], v183 offset:55296
	ds_read_b128 v[212:215], v183 offset:56320
	global_load_lds_dwordx4 v[216:217], off
	s_add_i32 m0, s44, 0x2000
	s_add_u32 s42, s42, 0x200080
	v_lshl_add_u64 v[216:217], v[218:219], 0, s[10:11]
	s_addc_u32 s43, s43, 0
	s_add_i32 s44, s68, s33
	global_load_lds_dwordx4 v[216:217], off
	v_lshl_add_u64 v[216:217], s[42:43], 0, v[156:157]
	s_mov_b32 m0, s44
	s_nop 0
	global_load_lds_dwordx4 v[216:217], off
	v_lshl_add_u64 v[216:217], s[42:43], 0, v[160:161]
	s_add_i32 m0, s44, 0x2000
	s_nop 0
	global_load_lds_dwordx4 v[216:217], off
	v_lshl_add_u64 v[216:217], v[220:221], 0, s[10:11]
	s_mov_b32 m0, s52
	s_nop 0
	global_load_lds_dwordx4 v[216:217], off
	v_lshl_add_u64 v[216:217], v[222:223], 0, s[10:11]
	s_mov_b32 m0, s53
	s_nop 0
	global_load_lds_dwordx4 v[216:217], off
	s_waitcnt vmcnt(8)
	s_waitcnt lgkmcnt(0)
	s_barrier
	s_waitcnt lgkmcnt(0)
	v_mfma_f32_16x16x32_bf16 v[62:65], v[130:133], v[184:187], v[62:65]
	v_mfma_f32_16x16x32_bf16 v[58:61], v[138:141], v[184:187], v[58:61]
	v_mfma_f32_16x16x32_bf16 v[46:49], v[130:133], v[192:195], v[46:49]
	v_mfma_f32_16x16x32_bf16 v[42:45], v[138:141], v[192:195], v[42:45]
	v_mfma_f32_16x16x32_bf16 v[38:41], v[130:133], v[200:203], v[38:41]
	v_mfma_f32_16x16x32_bf16 v[34:37], v[138:141], v[200:203], v[34:37]
	v_mfma_f32_16x16x32_bf16 v[22:25], v[130:133], v[208:211], v[22:25]
	v_mfma_f32_16x16x32_bf16 v[18:21], v[138:141], v[208:211], v[18:21]
	v_mfma_f32_16x16x32_bf16 v[62:65], v[134:137], v[188:191], v[62:65]
	v_mfma_f32_16x16x32_bf16 v[58:61], v[142:145], v[188:191], v[58:61]
	v_mfma_f32_16x16x32_bf16 v[46:49], v[134:137], v[196:199], v[46:49]
	v_mfma_f32_16x16x32_bf16 v[42:45], v[142:145], v[196:199], v[42:45]
	v_mfma_f32_16x16x32_bf16 v[38:41], v[134:137], v[204:207], v[38:41]
	v_mfma_f32_16x16x32_bf16 v[34:37], v[142:145], v[204:207], v[34:37]
	v_mfma_f32_16x16x32_bf16 v[22:25], v[134:137], v[212:215], v[22:25]
	v_mfma_f32_16x16x32_bf16 v[18:21], v[142:145], v[212:215], v[18:21]
	v_mfma_f32_16x16x32_bf16 v[54:57], v[146:149], v[184:187], v[54:57]
	v_mfma_f32_16x16x32_bf16 v[50:53], v[170:173], v[184:187], v[50:53]
	v_mfma_f32_16x16x32_bf16 v[30:33], v[146:149], v[192:195], v[30:33]
	v_mfma_f32_16x16x32_bf16 v[26:29], v[170:173], v[192:195], v[26:29]
	v_mfma_f32_16x16x32_bf16 v[14:17], v[146:149], v[200:203], v[14:17]
	v_mfma_f32_16x16x32_bf16 v[10:13], v[170:173], v[200:203], v[10:13]
	v_mfma_f32_16x16x32_bf16 v[6:9], v[146:149], v[208:211], v[6:9]
	v_mfma_f32_16x16x32_bf16 v[2:5], v[170:173], v[208:211], v[2:5]
	v_mfma_f32_16x16x32_bf16 v[54:57], v[150:153], v[188:191], v[54:57]
	v_mfma_f32_16x16x32_bf16 v[50:53], v[174:177], v[188:191], v[50:53]
	v_mfma_f32_16x16x32_bf16 v[30:33], v[150:153], v[196:199], v[30:33]
	v_mfma_f32_16x16x32_bf16 v[26:29], v[174:177], v[196:199], v[26:29]
	v_mfma_f32_16x16x32_bf16 v[14:17], v[150:153], v[204:207], v[14:17]
	v_mfma_f32_16x16x32_bf16 v[10:13], v[174:177], v[204:207], v[10:13]
	v_mfma_f32_16x16x32_bf16 v[6:9], v[150:153], v[212:215], v[6:9]
	v_mfma_f32_16x16x32_bf16 v[2:5], v[174:177], v[212:215], v[2:5]
	s_barrier
	s_add_i32 s66, s66, 2
	s_add_u32 s40, s40, 0x100
	s_addc_u32 s41, s41, 0
	s_add_u32 s64, s64, 0x100
	s_addc_u32 s65, s65, 0
	s_cmpk_gt_u32 s66, 0x7d
	s_cbranch_scc0 .LBB0_958
	s_and_b64 vcc, exec, s[12:13]
	s_cbranch_vccz .LBB0_961
	s_barrier
